# v42: bias-table staging off the mixer's entry path (skipped on WG<128, folded into the first chunk-MLP item on WG>=128), ctx/window attention prologue loads issued together, chunk-MLP row loads one it
# speedup vs baseline: 1.7429x; 1.0206x over previous
.Lgs3_done:
	s_mov_b64 exec, s[4:5]
	v_mov_b32_e32 v100, v174
	v_readlane_b32 s4, v255, 20
	s_movk_i32 s0, 0x744
	s_barrier
	s_mov_b64 s[76:77], s[56:57]
	v_readlane_b32 s5, v255, 21
	v_readlane_b32 s6, v255, 22
	v_readlane_b32 s7, v255, 23
	v_cmp_gt_i32_e32 vcc, s0, v100
	v_readlane_b32 s8, v255, 24
	v_readlane_b32 s9, v255, 25
	v_readlane_b32 s10, v255, 26
	v_readlane_b32 s11, v255, 27
	s_mov_b64 s[4:5], exec
	s_cmpk_lt_i32 s58, 0x80
	s_cbranch_scc1 .LBB0_160
	s_mul_i32 s30, s34, 0x744
	s_lshl_b64 s[0:1], s[30:31], 2
	s_add_u32 s6, s6, s0
	s_addc_u32 s7, s7, s1
	v_lshlrev_b32_e32 v0, 2, v100
	v_add_u32_e32 v2, 0x1000, v0
	v_mov_b32_e32 v47, 0
	v_cmp_gt_u32_e32 vcc, 0x144, v100
	global_load_dword v44, v0, s[6:7]
	global_load_dword v45, v0, s[6:7] offset:2048
	global_load_dword v46, v2, s[6:7]
	s_and_saveexec_b64 s[0:1], vcc
	global_load_dword v47, v2, s[6:7] offset:2048
	s_mov_b64 exec, s[4:5]
.LBB0_160:
	s_or_b64 exec, exec, s[4:5]
	v_readlane_b32 s80, v255, 0
	v_readlane_b32 s92, v255, 12
	v_readlane_b32 s93, v255, 13
	v_readlane_b32 s90, v255, 10
	v_readlane_b32 s91, v255, 11
	v_readlane_b32 s94, v255, 14
	v_readlane_b32 s95, v255, 15
	s_mov_b64 s[48:49], s[92:93]
	s_mov_b64 s[10:11], s[90:91]
	s_mov_b64 s[4:5], s[48:49]
	s_mov_b64 s[6:7], -1
	s_and_b64 vcc, exec, s[38:39]
	v_readlane_b32 s81, v255, 1
	v_readlane_b32 s82, v255, 2
	v_readlane_b32 s83, v255, 3
	v_readlane_b32 s84, v255, 4
	v_readlane_b32 s85, v255, 5
	v_readlane_b32 s86, v255, 6
	v_readlane_b32 s87, v255, 7
	v_readlane_b32 s88, v255, 8
	v_readlane_b32 s89, v255, 9
	s_mov_b64 s[50:51], s[94:95]
	s_cbranch_vccz .LBB0_162
	v_readlane_b32 s0, v255, 32
	s_sub_i32 s0, s0, s58
	s_ashr_i32 s1, s0, 31
	s_abs_i32 s0, s0
	v_readlane_b32 s2, v255, 34
	s_mul_hi_u32 s2, s0, s2
	v_readlane_b32 s8, v255, 33
	s_mul_i32 s6, s2, s8
	s_sub_i32 s0, s0, s6
	s_xor_b32 s1, s1, s33
	s_add_i32 s6, s2, 1
	s_sub_i32 s7, s0, s8
	s_cmp_ge_u32 s0, s8
	s_cselect_b32 s2, s6, s2
	s_cselect_b32 s0, s7, s0
	s_add_i32 s6, s2, 1
	s_cmp_ge_u32 s0, s8
	s_cselect_b32 s0, s6, s2
	s_xor_b32 s0, s0, s1
	s_sub_i32 s0, s0, s1
	s_mov_b64 s[6:7], 0

.LBB0_166:
	s_lshl_b32 s10, s11, 5
	s_and_b32 s10, s10, 0xffffff80
	v_add_u32_e32 v2, s10, v30
	v_mov_b64_e32 v[26:27], s[6:7]
	s_lshl_b32 s11, s11, 7
	v_mad_i64_i32 v[2:3], s[12:13], v2, s19, v[26:27]
	s_and_b32 s30, s11, 0x180
	v_lshl_add_u64 v[2:3], v[2:3], 0, s[30:31]
	v_lshl_add_u64 v[6:7], v[2:3], 0, v[0:1]
	s_cmp_eq_u32 s2, 0
	s_cbranch_scc0 .Lst_pf
	global_load_dwordx4 v[2:5], v[6:7], off offset:528
	global_load_dwordx4 v[6:9], v[6:7], off offset:512
.Lst_pf:
	v_lshl_add_u64 v[162:163], v[18:19], 0, s[30:31]
	v_lshlrev_b64 v[162:163], 9, v[162:163]
	v_lshl_add_u64 v[162:163], v[20:21], 0, v[162:163]
	global_load_dwordx4 v[196:199], v[162:163], off
	global_load_dwordx4 v[200:203], v[162:163], off offset:16
	global_load_dwordx4 v[204:207], v[162:163], off offset:64
	global_load_dwordx4 v[208:211], v[162:163], off offset:80
	global_load_dwordx4 v[212:215], v[162:163], off offset:128
	global_load_dwordx4 v[216:219], v[162:163], off offset:144
	global_load_dwordx4 v[220:223], v[162:163], off offset:192
	global_load_dwordx4 v[224:227], v[162:163], off offset:208
	global_load_dwordx4 v[228:231], v[162:163], off offset:256
	global_load_dwordx4 v[232:235], v[162:163], off offset:272
	global_load_dwordx4 v[236:239], v[162:163], off offset:320
	global_load_dwordx4 v[240:243], v[162:163], off offset:336
	global_load_dwordx4 v[244:247], v[162:163], off offset:384
	global_load_dwordx4 v[248:251], v[162:163], off offset:400
	global_load_dwordx4 v[48:51], v[162:163], off offset:448
	global_load_dwordx4 v[52:55], v[162:163], off offset:464
	v_add_u32_e32 v252, s30, v18
	v_ashrrev_i32_e32 v253, 31, v252
	v_lshl_add_u64 v[252:253], v[252:253], 2, s[4:5]
	global_load_dword v68, v[252:253], off
	v_add_u32_e32 v164, s10, v18
	v_mov_b64_e32 v[56:57], s[6:7]
	v_mov_b32_e32 v58, v22
	v_mov_b32_e32 v59, v1
	v_mad_i64_i32 v[164:165], s[12:13], v164, s19, v[56:57]
	v_lshl_add_u64 v[164:165], v[164:165], 0, s[30:31]
	v_lshl_add_u64 v[164:165], v[164:165], 0, v[58:59]
	global_load_dwordx2 v[60:61], v[164:165], off
	global_load_dwordx2 v[166:167], v[164:165], off offset:1024
	global_load_dwordx2 v[62:63], v[164:165], off offset:16
	global_load_dwordx2 v[168:169], v[164:165], off offset:1040
	global_load_dwordx2 v[64:65], v[164:165], off offset:32
	global_load_dwordx2 v[170:171], v[164:165], off offset:1056
	global_load_dwordx2 v[66:67], v[164:165], off offset:48
	global_load_dwordx2 v[172:173], v[164:165], off offset:1072
	s_add_i32 s74, s1, 1
	s_lshl_b32 s75, s74, 5
	s_and_b32 s75, s75, 0xffffff80
	s_lshl_b32 s74, s74, 7
	s_and_b32 s74, s74, 0x180
	v_add_u32_e32 v84, s75, v30
	v_mad_i64_i32 v[84:85], s[12:13], v84, s19, v[26:27]
	s_mov_b32 s75, 0
	v_lshl_add_u64 v[84:85], v[84:85], 0, s[74:75]
	v_lshl_add_u64 v[84:85], v[84:85], 0, v[0:1]
	global_load_dwordx4 v[86:89], v[84:85], off offset:528
	global_load_dwordx4 v[90:93], v[84:85], off offset:512
	s_add_i32 s2, s2, 1
	s_add_i32 s1, s1, 1
	s_add_i32 s0, s0, -1
	s_cmp_eq_u32 s0, 0
	v_cmp_eq_u32_e64 s[12:13], s2, 1
	s_nop 1
	s_mov_b64 vcc, s[12:13]
	s_cbranch_vccz .Lst_copy
	s_waitcnt vmcnt(27)
	s_branch .Lst_go
.Lst_copy:
	s_waitcnt vmcnt(31)
	v_mov_b32_e32 v2, v86
	v_mov_b32_e32 v3, v87
	v_mov_b32_e32 v4, v88
	v_mov_b32_e32 v5, v89
	v_mov_b32_e32 v6, v90
	v_mov_b32_e32 v7, v91
	v_mov_b32_e32 v8, v92
	v_mov_b32_e32 v9, v93
.Lst_go:
	v_lshlrev_b32_e32 v42, 16, v2
	v_cmp_eq_u32_e64 s[12:13], s2, 1
	s_nop 1
	s_mov_b64 vcc, s[12:13]
	s_cbranch_vccz .Lrpb_done
	v_mul_f32_e32 v44, 0x3fb8aa3b, v44
	v_mul_f32_e32 v45, 0x3fb8aa3b, v45
	v_mul_f32_e32 v46, 0x3fb8aa3b, v46
	v_mul_f32_e32 v47, 0x3fb8aa3b, v47
	v_lshlrev_b32_e32 v56, 2, v100
	s_nop 0
	ds_write2st64_b32 v56, v44, v45 offset1:8
	ds_write2st64_b32 v56, v46, v47 offset0:16 offset1:24
.Lrpb_done:
	v_lshlrev_b32_e32 v16, 16, v6
	v_and_b32_e32 v17, 0xffff0000, v6
	v_pk_mul_f32 v[24:25], v[16:17], v[16:17]
	v_lshlrev_b32_e32 v6, 16, v7
	v_and_b32_e32 v7, 0xffff0000, v7
	v_pk_mul_f32 v[28:29], v[6:7], v[6:7]
	v_add_f32_e32 v23, v24, v25
	v_lshlrev_b32_e32 v36, 16, v8
	v_and_b32_e32 v37, 0xffff0000, v8
	v_add_f32_e32 v23, v28, v23
	v_pk_mul_f32 v[38:39], v[36:37], v[36:37]
	v_add_f32_e32 v23, v29, v23
	v_lshlrev_b32_e32 v8, 16, v9
	v_and_b32_e32 v9, 0xffff0000, v9
	v_add_f32_e32 v23, v38, v23
	v_pk_mul_f32 v[40:41], v[8:9], v[8:9]
	v_add_f32_e32 v23, v39, v23
	v_and_b32_e32 v43, 0xffff0000, v2
	v_add_f32_e32 v23, v40, v23
	v_pk_mul_f32 v[44:45], v[42:43], v[42:43]
	v_add_f32_e32 v23, v41, v23
	v_lshlrev_b32_e32 v2, 16, v3
	v_and_b32_e32 v3, 0xffff0000, v3
	v_add_f32_e32 v23, v44, v23
	v_pk_mul_f32 v[46:47], v[2:3], v[2:3]
	v_add_f32_e32 v23, v45, v23
	v_and_b32_e32 v10, 0xffff0000, v4
	v_lshlrev_b32_e32 v11, 16, v4
	v_add_f32_e32 v23, v46, v23
	v_pk_mul_f32 v[12:13], v[10:11], v[10:11]
	v_add_f32_e32 v23, v47, v23
	v_and_b32_e32 v4, 0xffff0000, v5
	v_lshlrev_b32_e32 v5, 16, v5
	v_add_f32_e32 v13, v13, v23
	v_pk_mul_f32 v[14:15], v[4:5], v[4:5]
	v_add_f32_e32 v12, v12, v13
	v_add_f32_e32 v12, v15, v12
	v_add_f32_e32 v12, v14, v12
	ds_bpermute_b32 v13, v31, v12
	v_add_u32_e32 v28, s10, v18
	v_mad_i64_i32 v[26:27], s[10:11], v28, s19, v[26:27]
	v_lshl_add_u64 v[26:27], v[26:27], 0, s[30:31]
	s_waitcnt lgkmcnt(0)
	v_add_f32_e32 v12, v12, v13
	ds_bpermute_b32 v13, v32, v12
	v_mov_b32_e32 v23, v1
	v_lshl_add_u64 v[26:27], v[26:27], 0, v[22:23]
	v_ashrrev_i32_e32 v29, 31, v28
	v_lshlrev_b64 v[28:29], 11, v[28:29]
	s_waitcnt lgkmcnt(0)
	v_add_f32_e32 v12, v12, v13
	v_fmamk_f32 v12, v12, 0x3c800000, v175
	v_cmp_gt_f32_e32 vcc, s15, v12
	v_mul_f32_e32 v13, 0x4b800000, v12
	v_lshl_add_u64 v[28:29], s[8:9], 0, v[28:29]
	v_cndmask_b32_e32 v12, v12, v13, vcc
	v_rsq_f32_e32 v12, v12
	v_lshl_add_u64 v[28:29], v[28:29], 0, s[30:31]
	v_mul_f32_e32 v13, 0x45800000, v12
	v_cndmask_b32_e32 v12, v12, v13, vcc
	v_pk_mul_f32 v[14:15], v[12:13], v[16:17] op_sel_hi:[0,1]
	v_cvt_pk_bf16_f32 v13, v14, v15
	v_pk_mul_f32 v[6:7], v[12:13], v[6:7] op_sel_hi:[0,1]
	v_cvt_pk_bf16_f32 v6, v6, v7
	ds_write_b16 v34, v13 offset:8192
	ds_write_b16_d16_hi v34, v13 offset:8464
	ds_write_b16 v34, v6 offset:8736
	ds_write_b16_d16_hi v34, v6 offset:9008
	v_pk_mul_f32 v[6:7], v[12:13], v[36:37] op_sel_hi:[0,1]
	v_cvt_pk_bf16_f32 v6, v6, v7
	ds_write_b16 v34, v6 offset:9280
	ds_write_b16_d16_hi v34, v6 offset:9552
	v_pk_mul_f32 v[6:7], v[12:13], v[8:9] op_sel_hi:[0,1]
	v_cvt_pk_bf16_f32 v6, v6, v7
	ds_write_b16 v34, v6 offset:9824
	ds_write_b16_d16_hi v34, v6 offset:10096
	v_pk_mul_f32 v[6:7], v[12:13], v[42:43] op_sel_hi:[0,1]
	v_pk_mul_f32 v[2:3], v[12:13], v[2:3] op_sel_hi:[0,1]
	v_cvt_pk_bf16_f32 v6, v6, v7
	v_cvt_pk_bf16_f32 v2, v2, v3
	ds_write_b16 v34, v6 offset:10368
	ds_write_b16_d16_hi v34, v6 offset:10640
	ds_write_b16 v34, v2 offset:10912
	ds_write_b16_d16_hi v34, v2 offset:11184
	v_pk_mul_f32 v[2:3], v[12:13], v[10:11] op_sel_hi:[0,1]
	v_pk_mov_b32 v[2:3], v[2:3], v[2:3] op_sel:[1,0]
	s_nop 0
	v_cvt_pk_bf16_f32 v2, v2, v3
	ds_write_b16 v34, v2 offset:11456
	ds_write_b16_d16_hi v34, v2 offset:11728
	v_pk_mul_f32 v[2:3], v[12:13], v[4:5] op_sel_hi:[0,1]
	v_pk_mov_b32 v[2:3], v[2:3], v[2:3] op_sel:[1,0]
	s_nop 0
	v_cvt_pk_bf16_f32 v2, v2, v3
	ds_write_b16 v34, v2 offset:12000
	ds_write_b16_d16_hi v34, v2 offset:12272
	v_lshl_add_u64 v[2:3], v[18:19], 0, s[30:31]
	v_lshlrev_b64 v[2:3], 9, v[2:3]
	v_lshl_add_u64 v[24:25], v[20:21], 0, v[2:3]
	s_waitcnt lgkmcnt(0)
	s_barrier
	s_waitcnt vmcnt(11)
	ds_read_b128 v[36:39], v33 offset:8192
	ds_read_b128 v[40:43], v33 offset:8224
	v_cvt_pk_bf16_f32 v44, v196, v197
	v_cvt_pk_bf16_f32 v45, v198, v199
	v_cvt_pk_bf16_f32 v46, v200, v201
	v_cvt_pk_bf16_f32 v47, v202, v203
	s_waitcnt lgkmcnt(1)
	s_nop 1
	v_mfma_f32_32x32x16_bf16 v[2:17], v[36:39], v[44:47], 0
	ds_read_b128 v[36:39], v33 offset:8256
	v_cvt_pk_bf16_f32 v56, v204, v205
	v_cvt_pk_bf16_f32 v57, v206, v207
	v_cvt_pk_bf16_f32 v58, v208, v209
	v_cvt_pk_bf16_f32 v59, v210, v211
	s_waitcnt lgkmcnt(1)
	s_nop 1
	v_mfma_f32_32x32x16_bf16 v[2:17], v[40:43], v[56:59], v[2:17]
	ds_read_b128 v[40:43], v33 offset:8288
	v_cvt_pk_bf16_f32 v44, v212, v213
	v_cvt_pk_bf16_f32 v45, v214, v215
	v_cvt_pk_bf16_f32 v46, v216, v217
	v_cvt_pk_bf16_f32 v47, v218, v219
	s_waitcnt lgkmcnt(1)
	s_nop 1
	v_mfma_f32_32x32x16_bf16 v[2:17], v[36:39], v[44:47], v[2:17]
	ds_read_b128 v[36:39], v33 offset:8320
	v_cvt_pk_bf16_f32 v56, v220, v221
	v_cvt_pk_bf16_f32 v57, v222, v223
	v_cvt_pk_bf16_f32 v58, v224, v225
	v_cvt_pk_bf16_f32 v59, v226, v227
	s_waitcnt lgkmcnt(1)
	s_nop 1
	v_mfma_f32_32x32x16_bf16 v[2:17], v[40:43], v[56:59], v[2:17]
	ds_read_b128 v[40:43], v33 offset:8352
	v_cvt_pk_bf16_f32 v44, v228, v229
	v_cvt_pk_bf16_f32 v45, v230, v231
	v_cvt_pk_bf16_f32 v46, v232, v233
	v_cvt_pk_bf16_f32 v47, v234, v235
	s_waitcnt lgkmcnt(1)
	s_nop 1
	v_mfma_f32_32x32x16_bf16 v[2:17], v[36:39], v[44:47], v[2:17]
	ds_read_b128 v[36:39], v33 offset:8384
	v_cvt_pk_bf16_f32 v56, v236, v237
	v_cvt_pk_bf16_f32 v57, v238, v239
	v_cvt_pk_bf16_f32 v58, v240, v241
	v_cvt_pk_bf16_f32 v59, v242, v243
	s_waitcnt lgkmcnt(1)
	s_nop 1
	v_mfma_f32_32x32x16_bf16 v[2:17], v[40:43], v[56:59], v[2:17]
	ds_read_b128 v[40:43], v33 offset:8416
	v_cvt_pk_bf16_f32 v44, v244, v245
	v_cvt_pk_bf16_f32 v45, v246, v247
	v_cvt_pk_bf16_f32 v46, v248, v249
	v_cvt_pk_bf16_f32 v47, v250, v251
	s_waitcnt lgkmcnt(1)
	s_nop 1
	v_mfma_f32_32x32x16_bf16 v[2:17], v[36:39], v[44:47], v[2:17]
	v_cvt_pk_bf16_f32 v56, v48, v49
	v_cvt_pk_bf16_f32 v57, v50, v51
	v_cvt_pk_bf16_f32 v58, v52, v53
	v_cvt_pk_bf16_f32 v59, v54, v55
	s_waitcnt lgkmcnt(0)
	s_nop 1
	v_mfma_f32_32x32x16_bf16 v[2:17], v[40:43], v[56:59], v[2:17]
	s_waitcnt vmcnt(2)
	s_nop 7
	s_nop 3
	v_mov_b32_e32 v24, v68
	v_mov_b32_e32 v36, v60
	v_mov_b32_e32 v37, v61
	v_mov_b32_e32 v38, v166
	v_mov_b32_e32 v39, v167
	v_lshlrev_b32_e32 v42, 16, v36
	v_lshlrev_b32_e32 v25, 16, v38
	v_and_b32_e32 v35, 0xffff0000, v38
	v_mul_f32_e32 v38, 0xbfb8aa3b, v25
	v_and_b32_e32 v43, 0xffff0000, v36
	v_mul_f32_e32 v36, 0xbfb8aa3b, v35
	v_exp_f32_e32 v40, v38
	v_exp_f32_e32 v41, v36
	v_pk_add_f32 v[2:3], v[24:25], v[2:3] op_sel_hi:[0,1]
	v_pk_mul_f32 v[2:3], v[2:3], v[42:43]
	v_pk_add_f32 v[40:41], v[40:41], 1.0 op_sel_hi:[1,0]
	s_nop 0
	v_div_scale_f32 v36, s[10:11], v41, v41, v35
	v_rcp_f32_e32 v38, v36
	s_nop 0
	v_fma_f32 v42, -v36, v38, 1.0
	v_fmac_f32_e32 v38, v42, v38
	v_div_scale_f32 v42, vcc, v35, v41, v35
	v_mul_f32_e32 v43, v42, v38
	v_fma_f32 v44, -v36, v43, v42
	v_fmac_f32_e32 v43, v44, v38
	v_fma_f32 v36, -v36, v43, v42
	v_div_fmas_f32 v36, v36, v38, v43
	v_div_fixup_f32 v41, v36, v41, v35
	v_div_scale_f32 v35, s[10:11], v40, v40, v25
	v_rcp_f32_e32 v36, v35
	s_nop 0
	v_fma_f32 v38, -v35, v36, 1.0
	v_fmac_f32_e32 v36, v38, v36
	v_div_scale_f32 v38, vcc, v25, v40, v25
	v_mul_f32_e32 v42, v38, v36
	v_fma_f32 v43, -v35, v42, v38
	v_fmac_f32_e32 v42, v43, v36
	v_fma_f32 v35, -v35, v42, v38
	v_div_fmas_f32 v35, v35, v36, v42
	v_div_fixup_f32 v40, v35, v40, v25
	v_lshlrev_b32_e32 v25, 16, v39
	v_and_b32_e32 v35, 0xffff0000, v39
	v_mul_f32_e32 v36, 0xbfb8aa3b, v25
	v_lshlrev_b32_e32 v38, 16, v37
	v_and_b32_e32 v39, 0xffff0000, v37
	v_mul_f32_e32 v37, 0xbfb8aa3b, v35
	v_exp_f32_e32 v36, v36
	v_exp_f32_e32 v37, v37
	v_pk_add_f32 v[4:5], v[24:25], v[4:5] op_sel_hi:[0,1]
	v_pk_mul_f32 v[4:5], v[4:5], v[38:39]
	v_pk_mul_f32 v[2:3], v[2:3], v[40:41]
	v_pk_add_f32 v[36:37], v[36:37], 1.0 op_sel_hi:[1,0]
	s_nop 0
	v_div_scale_f32 v38, s[10:11], v37, v37, v35
	v_rcp_f32_e32 v39, v38
	s_nop 0
	v_fma_f32 v40, -v38, v39, 1.0
	v_fmac_f32_e32 v39, v40, v39
	v_div_scale_f32 v40, vcc, v35, v37, v35
	v_mul_f32_e32 v41, v40, v39
	v_fma_f32 v42, -v38, v41, v40
	v_fmac_f32_e32 v41, v42, v39
	v_fma_f32 v38, -v38, v41, v40
	v_div_fmas_f32 v38, v38, v39, v41
	v_div_fixup_f32 v37, v38, v37, v35
	v_div_scale_f32 v35, s[10:11], v36, v36, v25
	v_rcp_f32_e32 v38, v35
	s_nop 0
	v_fma_f32 v39, -v35, v38, 1.0
	v_fmac_f32_e32 v38, v39, v38
	v_div_scale_f32 v39, vcc, v25, v36, v25
	v_mul_f32_e32 v40, v39, v38
	v_fma_f32 v41, -v35, v40, v39
	v_fmac_f32_e32 v40, v41, v38
	v_fma_f32 v35, -v35, v40, v39
	v_div_fmas_f32 v35, v35, v38, v40
	v_div_fixup_f32 v36, v35, v36, v25
	v_pk_mul_f32 v[4:5], v[4:5], v[36:37]
	v_cvt_pk_bf16_f32 v36, v2, v3
	v_cvt_pk_bf16_f32 v37, v4, v5
	v_lshl_add_u64 v[2:3], v[28:29], 0, v[22:23]
	global_store_dwordx2 v[2:3], v[36:37], off
	v_mov_b32_e32 v4, v62
	v_mov_b32_e32 v5, v63
	v_mov_b32_e32 v28, v168
	v_mov_b32_e32 v29, v169
	v_lshlrev_b32_e32 v38, 16, v4
	v_lshlrev_b32_e32 v23, 16, v28
	v_and_b32_e32 v25, 0xffff0000, v28
	v_mul_f32_e32 v28, 0xbfb8aa3b, v23
	v_and_b32_e32 v39, 0xffff0000, v4
	v_mul_f32_e32 v4, 0xbfb8aa3b, v25
	v_exp_f32_e32 v36, v28
	v_exp_f32_e32 v37, v4
	v_pk_add_f32 v[6:7], v[24:25], v[6:7] op_sel_hi:[0,1]
	v_pk_mul_f32 v[6:7], v[6:7], v[38:39]
	v_pk_add_f32 v[36:37], v[36:37], 1.0 op_sel_hi:[1,0]
	s_nop 0
	v_div_scale_f32 v4, s[10:11], v37, v37, v25
	v_rcp_f32_e32 v28, v4
	s_nop 0
	v_fma_f32 v35, -v4, v28, 1.0
	v_fmac_f32_e32 v28, v35, v28
	v_div_scale_f32 v35, vcc, v25, v37, v25
	v_mul_f32_e32 v38, v35, v28
	v_fma_f32 v39, -v4, v38, v35
	v_fmac_f32_e32 v38, v39, v28
	v_fma_f32 v4, -v4, v38, v35
	v_div_fmas_f32 v4, v4, v28, v38
	v_div_fixup_f32 v37, v4, v37, v25
	v_div_scale_f32 v4, s[10:11], v36, v36, v23
	v_rcp_f32_e32 v25, v4
	s_nop 0
	v_fma_f32 v28, -v4, v25, 1.0
	v_fmac_f32_e32 v25, v28, v25
	v_div_scale_f32 v28, vcc, v23, v36, v23
	v_mul_f32_e32 v35, v28, v25
	v_fma_f32 v38, -v4, v35, v28
	v_fmac_f32_e32 v35, v38, v25
	v_fma_f32 v4, -v4, v35, v28
	v_div_fmas_f32 v4, v4, v25, v35
	v_div_fixup_f32 v36, v4, v36, v23
	v_lshlrev_b32_e32 v23, 16, v29
	v_and_b32_e32 v25, 0xffff0000, v29
	v_mul_f32_e32 v4, 0xbfb8aa3b, v23
	v_lshlrev_b32_e32 v28, 16, v5
	v_and_b32_e32 v29, 0xffff0000, v5
	v_mul_f32_e32 v5, 0xbfb8aa3b, v25
	v_exp_f32_e32 v4, v4
	v_exp_f32_e32 v5, v5
	v_pk_add_f32 v[8:9], v[24:25], v[8:9] op_sel_hi:[0,1]
	v_pk_mul_f32 v[8:9], v[8:9], v[28:29]
	v_pk_mul_f32 v[6:7], v[6:7], v[36:37]
	v_pk_add_f32 v[4:5], v[4:5], 1.0 op_sel_hi:[1,0]
	v_cvt_pk_bf16_f32 v6, v6, v7
	v_div_scale_f32 v28, s[10:11], v5, v5, v25
	v_rcp_f32_e32 v29, v28
	s_nop 0
	v_fma_f32 v35, -v28, v29, 1.0
	v_fmac_f32_e32 v29, v35, v29
	v_div_scale_f32 v35, vcc, v25, v5, v25
	v_mul_f32_e32 v36, v35, v29
	v_fma_f32 v37, -v28, v36, v35
	v_fmac_f32_e32 v36, v37, v29
	v_fma_f32 v28, -v28, v36, v35
	v_div_fmas_f32 v28, v28, v29, v36
	v_div_fixup_f32 v5, v28, v5, v25
	v_div_scale_f32 v25, s[10:11], v4, v4, v23
	v_rcp_f32_e32 v28, v25
	s_nop 0
	v_fma_f32 v29, -v25, v28, 1.0
	v_fmac_f32_e32 v28, v29, v28
	v_div_scale_f32 v29, vcc, v23, v4, v23
	v_mul_f32_e32 v35, v29, v28
	v_fma_f32 v36, -v25, v35, v29
	v_fmac_f32_e32 v35, v36, v28
	v_fma_f32 v25, -v25, v35, v29
	v_div_fmas_f32 v25, v25, v28, v35
	v_div_fixup_f32 v4, v25, v4, v23
	v_pk_mul_f32 v[4:5], v[8:9], v[4:5]
	v_pk_add_f32 v[10:11], v[24:25], v[10:11] op_sel_hi:[0,1]
	v_cvt_pk_bf16_f32 v7, v4, v5
	global_store_dwordx2 v[2:3], v[6:7], off offset:16
	v_mov_b32_e32 v4, v64
	v_mov_b32_e32 v5, v65
	v_mov_b32_e32 v6, v170
	v_mov_b32_e32 v7, v171
	v_lshlrev_b32_e32 v28, 16, v4
	v_lshlrev_b32_e32 v23, 16, v6
	v_and_b32_e32 v6, 0xffff0000, v6
	v_mul_f32_e32 v8, 0xbfb8aa3b, v23
	v_and_b32_e32 v29, 0xffff0000, v4
	v_mul_f32_e32 v4, 0xbfb8aa3b, v6
	v_exp_f32_e32 v8, v8
	v_exp_f32_e32 v9, v4
	v_pk_mul_f32 v[10:11], v[10:11], v[28:29]
	v_pk_add_f32 v[8:9], v[8:9], 1.0 op_sel_hi:[1,0]
	s_nop 0
	v_div_scale_f32 v4, s[10:11], v9, v9, v6
	v_rcp_f32_e32 v25, v4
	s_nop 0
	v_fma_f32 v28, -v4, v25, 1.0
	v_fmac_f32_e32 v25, v28, v25
	v_div_scale_f32 v28, vcc, v6, v9, v6
	v_mul_f32_e32 v29, v28, v25
	v_fma_f32 v35, -v4, v29, v28
	v_fmac_f32_e32 v29, v35, v25
	v_fma_f32 v4, -v4, v29, v28
	v_div_fmas_f32 v4, v4, v25, v29
	v_div_fixup_f32 v9, v4, v9, v6
	v_div_scale_f32 v4, s[10:11], v8, v8, v23
	v_rcp_f32_e32 v6, v4
	s_nop 0
	v_fma_f32 v25, -v4, v6, 1.0
	v_fmac_f32_e32 v6, v25, v6
	v_div_scale_f32 v25, vcc, v23, v8, v23
	v_mul_f32_e32 v28, v25, v6
	v_fma_f32 v29, -v4, v28, v25
	v_fmac_f32_e32 v28, v29, v6
	v_fma_f32 v4, -v4, v28, v25
	v_div_fmas_f32 v4, v4, v6, v28
	v_div_fixup_f32 v8, v4, v8, v23
	v_lshlrev_b32_e32 v23, 16, v7
	v_and_b32_e32 v25, 0xffff0000, v7
	v_mul_f32_e32 v4, 0xbfb8aa3b, v23
	v_lshlrev_b32_e32 v6, 16, v5
	v_and_b32_e32 v7, 0xffff0000, v5
	v_mul_f32_e32 v5, 0xbfb8aa3b, v25
	v_exp_f32_e32 v4, v4
	v_exp_f32_e32 v5, v5
	v_pk_mul_f32 v[8:9], v[10:11], v[8:9]
	v_pk_add_f32 v[10:11], v[24:25], v[12:13] op_sel_hi:[0,1]
	v_pk_mul_f32 v[6:7], v[10:11], v[6:7]
	v_pk_add_f32 v[4:5], v[4:5], 1.0 op_sel_hi:[1,0]
	s_nop 0
	v_div_scale_f32 v10, s[10:11], v5, v5, v25
	v_rcp_f32_e32 v11, v10
	s_nop 0
	v_fma_f32 v12, -v10, v11, 1.0
	v_fmac_f32_e32 v11, v12, v11
	v_div_scale_f32 v12, vcc, v25, v5, v25
	v_mul_f32_e32 v13, v12, v11
	v_fma_f32 v28, -v10, v13, v12
	v_fmac_f32_e32 v13, v28, v11
	v_fma_f32 v10, -v10, v13, v12
	v_div_fmas_f32 v10, v10, v11, v13
	v_div_fixup_f32 v5, v10, v5, v25
	v_div_scale_f32 v10, s[10:11], v4, v4, v23
	v_rcp_f32_e32 v11, v10
	s_nop 0
	v_fma_f32 v12, -v10, v11, 1.0
	v_fmac_f32_e32 v11, v12, v11
	v_div_scale_f32 v12, vcc, v23, v4, v23
	v_mul_f32_e32 v13, v12, v11
	v_fma_f32 v25, -v10, v13, v12
	v_fmac_f32_e32 v13, v25, v11
	v_fma_f32 v10, -v10, v13, v12
	v_div_fmas_f32 v10, v10, v11, v13
	v_div_fixup_f32 v4, v10, v4, v23
	v_pk_mul_f32 v[4:5], v[6:7], v[4:5]
	v_cvt_pk_bf16_f32 v6, v8, v9
	v_cvt_pk_bf16_f32 v7, v4, v5
	global_store_dwordx2 v[2:3], v[6:7], off offset:32
	v_mov_b32_e32 v4, v66
	v_mov_b32_e32 v5, v67
	v_mov_b32_e32 v6, v172
	v_mov_b32_e32 v7, v173
	v_pk_add_f32 v[12:13], v[24:25], v[14:15] op_sel_hi:[0,1]
	v_lshlrev_b32_e32 v10, 16, v4
	v_lshlrev_b32_e32 v23, 16, v6
	v_and_b32_e32 v6, 0xffff0000, v6
	v_mul_f32_e32 v8, 0xbfb8aa3b, v23
	v_and_b32_e32 v11, 0xffff0000, v4
	v_mul_f32_e32 v4, 0xbfb8aa3b, v6
	v_exp_f32_e32 v8, v8
	v_exp_f32_e32 v9, v4
	v_pk_mul_f32 v[10:11], v[12:13], v[10:11]
	v_pk_add_f32 v[8:9], v[8:9], 1.0 op_sel_hi:[1,0]
	s_nop 0
	v_div_scale_f32 v4, s[10:11], v9, v9, v6
	v_rcp_f32_e32 v12, v4
	s_nop 0
	v_fma_f32 v13, -v4, v12, 1.0
	v_fmac_f32_e32 v12, v13, v12
	v_div_scale_f32 v13, vcc, v6, v9, v6
	v_mul_f32_e32 v14, v13, v12
	v_fma_f32 v15, -v4, v14, v13
	v_fmac_f32_e32 v14, v15, v12
	v_fma_f32 v4, -v4, v14, v13
	v_div_fmas_f32 v4, v4, v12, v14
	v_div_fixup_f32 v9, v4, v9, v6
	v_div_scale_f32 v4, s[10:11], v8, v8, v23
	v_rcp_f32_e32 v6, v4
	s_nop 0
	v_fma_f32 v12, -v4, v6, 1.0
	v_fmac_f32_e32 v6, v12, v6
	v_div_scale_f32 v12, vcc, v23, v8, v23
	v_mul_f32_e32 v13, v12, v6
	v_fma_f32 v14, -v4, v13, v12
	v_fmac_f32_e32 v13, v14, v6
	v_fma_f32 v4, -v4, v13, v12
	v_div_fmas_f32 v4, v4, v6, v13
	v_lshlrev_b32_e32 v12, 16, v7
	v_and_b32_e32 v13, 0xffff0000, v7
	v_div_fixup_f32 v8, v4, v8, v23
	v_mul_f32_e32 v4, 0xbfb8aa3b, v12
	v_lshlrev_b32_e32 v6, 16, v5
	v_and_b32_e32 v7, 0xffff0000, v5
	v_mul_f32_e32 v5, 0xbfb8aa3b, v13
	v_exp_f32_e32 v4, v4
	v_exp_f32_e32 v5, v5
	v_pk_mul_f32 v[8:9], v[10:11], v[8:9]
	v_pk_add_f32 v[10:11], v[24:25], v[16:17] op_sel_hi:[0,1]
	v_pk_mul_f32 v[6:7], v[10:11], v[6:7]
	v_pk_add_f32 v[4:5], v[4:5], 1.0 op_sel_hi:[1,0]
	s_nop 0
	v_div_scale_f32 v10, s[10:11], v5, v5, v13
	v_rcp_f32_e32 v11, v10
	s_nop 0
	v_fma_f32 v14, -v10, v11, 1.0
	v_fmac_f32_e32 v11, v14, v11
	v_div_scale_f32 v14, vcc, v13, v5, v13
	v_mul_f32_e32 v15, v14, v11
	v_fma_f32 v16, -v10, v15, v14
	v_fmac_f32_e32 v15, v16, v11
	v_fma_f32 v10, -v10, v15, v14
	v_div_fmas_f32 v10, v10, v11, v15
	v_div_fixup_f32 v5, v10, v5, v13
	v_div_scale_f32 v10, s[10:11], v4, v4, v12
	v_rcp_f32_e32 v11, v10
	s_nop 0
	v_fma_f32 v13, -v10, v11, 1.0
	v_fmac_f32_e32 v11, v13, v11
	v_div_scale_f32 v13, vcc, v12, v4, v12
	v_mul_f32_e32 v14, v13, v11
	v_fma_f32 v15, -v10, v14, v13
	v_fmac_f32_e32 v14, v15, v11
	v_fma_f32 v10, -v10, v14, v13
	v_div_fmas_f32 v10, v10, v11, v14
	v_div_fixup_f32 v4, v10, v4, v12
	v_pk_mul_f32 v[4:5], v[6:7], v[4:5]
	v_cvt_pk_bf16_f32 v6, v8, v9
	v_cvt_pk_bf16_f32 v7, v4, v5
	global_store_dwordx2 v[2:3], v[6:7], off offset:48
	s_barrier
	s_cbranch_scc1 .LBB0_169

.LBB0_169:
	s_waitcnt vmcnt(0)
	s_cmpk_lt_i32 s58, 0x80
	v_readlane_b32 s80, v255, 0
	v_lshl_add_u32 v58, s58, 9, v100
	s_cselect_b64 s[0:1], -1, 0
	s_mov_b32 s2, 0x60000
	v_readlane_b32 s94, v255, 14
	v_readlane_b32 s95, v255, 15
	s_or_b64 s[0:1], s[42:43], s[0:1]
	v_cmp_gt_i32_e32 vcc, s2, v58
	s_mov_b64 s[10:11], s[94:95]
	s_and_b64 s[0:1], s[0:1], vcc
	v_readlane_b32 s81, v255, 1
	v_readlane_b32 s82, v255, 2
	v_readlane_b32 s83, v255, 3
	v_readlane_b32 s84, v255, 4
	v_readlane_b32 s85, v255, 5
	v_readlane_b32 s86, v255, 6
	v_readlane_b32 s87, v255, 7
	v_readlane_b32 s88, v255, 8
	v_readlane_b32 s89, v255, 9
	v_readlane_b32 s90, v255, 10
	v_readlane_b32 s91, v255, 11
	v_readlane_b32 s92, v255, 12
	v_readlane_b32 s93, v255, 13
	s_and_saveexec_b64 s[4:5], s[0:1]
	s_movk_i32 s20, 0x3ff
	v_readlane_b32 s30, v255, 61
	v_readlane_b32 s17, v255, 59
	v_readlane_b32 s21, v255, 60
	s_cbranch_execz .LBB0_176
	s_mul_i32 s30, s34, 0x300
	s_lshl_b64 s[0:1], s[30:31], 2
	s_add_u32 s10, s10, s0
	v_lshlrev_b32_e32 v0, 3, v100
	v_readlane_b32 s30, v255, 61
	v_readlane_b32 s21, v255, 60
	v_readlane_b32 s17, v255, 59
	s_addc_u32 s11, s11, s1
	v_and_b32_e32 v59, 31, v100
	v_lshrrev_b32_e32 v58, 5, v100
	v_lshlrev_b32_e32 v60, 5, v59
	v_lshlrev_b32_e32 v59, 4, v59
	s_cmpk_lt_i32 s58, 0x80
	s_cselect_b32 s74, 6, 0
	s_cselect_b32 s1, 0, 0x2800
	s_lshl_b32 s0, s58, 4
	s_add_u32 s0, s0, s1
	v_add_u32_e32 v58, s0, v58
	s_cmp_eq_u32 s74, 0
	s_cbranch_scc1 .Lcv_done
	global_load_dwordx4 v[196:199], v60, s[10:11]
	global_load_dwordx4 v[200:203], v60, s[10:11] offset:16
	global_load_dwordx4 v[204:207], v60, s[10:11] offset:1024
	global_load_dwordx4 v[208:211], v60, s[10:11] offset:1040
	global_load_dwordx4 v[212:215], v60, s[10:11] offset:2048
	global_load_dwordx4 v[216:219], v60, s[10:11] offset:2064
	s_mov_b32 s22, 0xffff0000
	s_mov_b32 s23, 0xbfb8aa3b
	v_mov_b32_e32 v66, 0xff
	v_mov_b32_e32 v67, 0xfff
	v_mov_b32_e32 v68, 0x1c00
	v_cmp_lt_u32_e32 vcc, 0xfff, v58
	v_mad_u32_u24 v54, v58, v68, v59
	s_nop 0
	v_cndmask_b32_e32 v52, v66, v67, vcc
	v_and_b32_e32 v53, v52, v58
	v_cmp_ne_u32_e32 vcc, 0, v53
	s_nop 1
	v_cndmask_b32_e32 v55, 0, v68, vcc
	v_cmp_ne_u32_e32 vcc, v53, v52
	v_sub_u32_e32 v55, v54, v55
	s_nop 0
	v_cndmask_b32_e32 v56, 0, v68, vcc
	v_add_u32_e32 v56, v54, v56
	global_load_dwordx4 v[220:223], v54, s[6:7] offset:1536
	global_load_dwordx4 v[224:227], v54, s[6:7] offset:2048
	global_load_dwordx4 v[228:231], v54, s[6:7] offset:2560
	global_load_dwordx4 v[232:235], v54, s[6:7] offset:3072
	global_load_dwordx4 v[236:239], v55, s[6:7] offset:2048
	global_load_dwordx4 v[240:243], v55, s[6:7] offset:2560
	global_load_dwordx4 v[244:247], v56, s[6:7] offset:2048
	global_load_dwordx4 v[248:251], v56, s[6:7] offset:2560

.LBB0_185:
	s_lshl_b64 s[12:13], s[30:31], 1
	v_add_u32_e32 v0, s2, v70
	s_add_u32 s12, s6, s12
	v_or_b32_e32 v66, v0, v124
	s_addc_u32 s13, s7, s13
	v_and_b32_e32 v0, 0x70, v82
	v_lshl_add_u64 v[10:11], s[12:13], 0, v[0:1]
	v_and_b32_e32 v2, 0x1f0, v82
	v_mov_b32_e32 v3, v1
	v_readlane_b32 s12, v255, 35
	v_ashrrev_i32_e32 v105, 3, v100
	v_ashrrev_i32_e32 v18, 5, v100
	v_lshl_add_u64 v[12:13], s[44:45], 0, v[2:3]
	v_add_u32_e32 v16, s12, v2
	v_add_u32_e32 v2, s2, v105
	v_ashrrev_i32_e32 v19, 31, v18
	v_mad_i64_i32 v[2:3], s[12:13], v2, s19, v[10:11]
	v_lshlrev_b64 v[6:7], 9, v[18:19]
	global_load_dwordx4 v[196:199], v[2:3], off
	v_lshl_add_u64 v[6:7], v[12:13], 0, v[6:7]
	global_load_dwordx4 v[200:203], v[6:7], off
	s_movk_i32 s20, 0x90
	v_add_u32_e32 v14, 0, v0
	v_mul_lo_u32 v15, v105, s20
	v_add_u32_e32 v126, v14, v15
	s_movk_i32 s21, 0x210
	v_add_u32_e32 v83, 0x200, v100
	v_ashrrev_i32_e32 v127, 3, v83
	v_mul_lo_u32 v15, v127, s20
	v_add_u32_e32 v128, v14, v15
	s_lshl_b32 s30, s22, 1
	v_mov_b32_e32 v99, v1
	v_readlane_b32 s44, v255, 20
	v_readlane_b32 s45, v255, 21
	s_movk_i32 s17, 0x90
	s_mov_b64 s[22:23], s[44:45]
	s_andn2_b64 vcc, exec, s[4:5]
	v_readlane_b32 s46, v255, 22
	v_readlane_b32 s47, v255, 23
	v_readlane_b32 s48, v255, 24
	v_readlane_b32 s49, v255, 25
	v_readlane_b32 s50, v255, 26
	v_readlane_b32 s51, v255, 27
	v_mad_u64_u32 v[228:229], s[12:13], v18, s21, v[16:17]
	v_ashrrev_i32_e32 v18, 5, v83
	v_add_u32_e32 v2, s2, v127
	v_ashrrev_i32_e32 v19, 31, v18
	v_mad_i64_i32 v[2:3], s[12:13], v2, s19, v[10:11]
	v_lshlrev_b64 v[6:7], 9, v[18:19]
	global_load_dwordx4 v[204:207], v[2:3], off
	v_lshl_add_u64 v[6:7], v[12:13], 0, v[6:7]
	global_load_dwordx4 v[208:211], v[6:7], off
	v_mad_u64_u32 v[230:231], s[12:13], v18, s21, v[16:17]
	v_add_u32_e32 v6, 0x400, v100
	v_ashrrev_i32_e32 v15, 3, v6
	v_ashrrev_i32_e32 v18, 5, v6
	v_add_u32_e32 v2, s2, v15
	v_ashrrev_i32_e32 v19, 31, v18
	v_mad_i64_i32 v[2:3], s[12:13], v2, s19, v[10:11]
	v_lshlrev_b64 v[6:7], 9, v[18:19]
	global_load_dwordx4 v[212:215], v[2:3], off
	v_lshl_add_u64 v[6:7], v[12:13], 0, v[6:7]
	global_load_dwordx4 v[216:219], v[6:7], off
	v_mad_u64_u32 v[20:21], s[12:13], v15, s20, v[14:15]
	v_mad_u64_u32 v[232:233], s[12:13], v18, s21, v[16:17]
	v_add_u32_e32 v6, 0x600, v100
	v_ashrrev_i32_e32 v15, 3, v6
	v_add_u32_e32 v2, s2, v15
	v_mad_i64_i32 v[2:3], s[12:13], v2, s19, v[10:11]
	v_ashrrev_i32_e32 v10, 5, v6
	v_ashrrev_i32_e32 v11, 31, v10
	v_lshlrev_b64 v[6:7], 9, v[10:11]
	global_load_dwordx4 v[220:223], v[2:3], off
	v_lshl_add_u64 v[6:7], v[12:13], 0, v[6:7]
	global_load_dwordx4 v[224:227], v[6:7], off
	v_mad_u64_u32 v[12:13], s[12:13], v15, s20, v[14:15]
	s_movk_i32 s20, 0x210
	v_mad_u64_u32 v[234:235], s[12:13], v10, s21, v[16:17]
	v_mov_b64_e32 v[2:3], s[6:7]
	v_mad_i64_i32 v[68:69], s[12:13], v66, s19, v[2:3]
	v_lshl_add_u64 v[2:3], v[68:69], 0, s[30:31]
	s_mov_b32 s30, s1
	v_lshl_add_u64 v[2:3], s[30:31], 1, v[2:3]
	v_lshl_add_u64 v[2:3], v[2:3], 0, v[98:99]
	global_load_dwordx4 v[50:53], v[2:3], off
	global_load_dwordx4 v[54:57], v[2:3], off offset:32
	global_load_dwordx4 v[58:61], v[2:3], off offset:64
	global_load_dwordx4 v[62:65], v[2:3], off offset:96
	s_waitcnt vmcnt(11)
	ds_write_b128 v126, v[196:199] offset:32768
	s_waitcnt vmcnt(10)
	ds_write_b128 v228, v[200:203]
	s_waitcnt vmcnt(9)
	ds_write_b128 v128, v[204:207] offset:32768
	s_waitcnt vmcnt(8)
	ds_write_b128 v230, v[208:211]
	s_waitcnt vmcnt(7)
	ds_write_b128 v20, v[212:215] offset:32768
	s_waitcnt vmcnt(6)
	ds_write_b128 v232, v[216:219]
	s_waitcnt vmcnt(5)
	ds_write_b128 v12, v[220:223] offset:32768
	s_waitcnt vmcnt(4)
	ds_write_b128 v234, v[224:227]
	s_cbranch_vccnz .LBB0_188
	s_mov_b32 s79, s31
	s_lshl_b64 s[12:13], s[78:79], 2
	s_add_u32 s12, s22, s12
	s_addc_u32 s13, s23, s13
	s_lshl_b32 s0, s0, 2
	v_mov_b32_e32 v2, s0
	global_load_dword v2, v2, s[12:13]
	s_mov_b32 s2, 1.0
	s_waitcnt vmcnt(0)
	v_mul_f32_e32 v73, 0x3fb8aa3b, v2
	s_branch .LBB0_189

.LBB0_190:
	v_add_u32_e32 v80, v72, v98
	ds_read_b128 v[34:37], v80
	ds_read_b128 v[76:79], v80 offset:32
	v_mov_b32_e32 v85, v74
	v_add_u32_e32 v86, v71, v98
	v_add_u32_e32 v87, 0x11000, v86
	s_waitcnt vmcnt(3) lgkmcnt(1)
	v_mfma_f32_32x32x16_bf16 v[34:49], v[34:37], v[50:53], 0
	v_add_u32_e32 v88, 0x11020, v86
	v_add_u32_e32 v90, 0x15200, v86
	v_add_u32_e32 v94, 0x15220, v86
	s_add_i32 s1, s1, -1
	v_add_u32_e32 v71, 64, v71
	v_add_u32_e32 v72, 0x1200, v72
	s_cmp_eq_u32 s1, 0
	s_waitcnt vmcnt(2) lgkmcnt(0)
	v_mfma_f32_32x32x16_bf16 v[34:49], v[76:79], v[54:57], v[34:49]
	ds_read_b128 v[74:77], v80 offset:64
	ds_read_b128 v[78:81], v80 offset:96
	s_waitcnt vmcnt(1) lgkmcnt(1)
	v_mfma_f32_32x32x16_bf16 v[34:49], v[74:77], v[58:61], v[34:49]
	ds_read_b128 v[74:77], v87
	ds_read_b128 v[86:89], v88
	ds_read_b128 v[90:93], v90
	ds_read_b128 v[94:97], v94
	s_waitcnt vmcnt(0) lgkmcnt(4)
	v_mfma_f32_32x32x16_bf16 v[34:49], v[78:81], v[62:65], v[34:49]
	s_nop 11
	v_max3_f32 v78, v34, v35, v36
	v_max3_f32 v78, v78, v37, v38
	v_max3_f32 v78, v78, v39, v40
	v_max3_f32 v78, v78, v41, v42
	v_max3_f32 v78, v78, v43, v44
	v_max3_f32 v78, v78, v45, v46
	v_max3_f32 v78, v78, v47, v48
	v_max_f32_e32 v78, v78, v49
	v_mul_f32_e32 v78, 0x3e38aa3b, v78
	v_mov_b32_e32 v79, v78
	s_nop 1
	v_permlane32_swap_b32_e32 v78, v79
	s_waitcnt lgkmcnt(0)
	v_max3_f32 v78, v73, v78, v79
	v_fma_f32 v34, v34, s18, -v78
	v_sub_f32_e32 v73, v73, v78
	v_fma_f32 v35, v35, s18, -v78
	v_fma_f32 v36, v36, s18, -v78
	v_fma_f32 v37, v37, s18, -v78
	v_fma_f32 v38, v38, s18, -v78
	v_fma_f32 v39, v39, s18, -v78
	v_fma_f32 v40, v40, s18, -v78
	v_fma_f32 v41, v41, s18, -v78
	v_exp_f32_e32 v79, v34
	v_exp_f32_e32 v80, v35
	v_exp_f32_e32 v81, v36
	v_exp_f32_e32 v103, v37
	v_exp_f32_e32 v104, v38
	v_exp_f32_e32 v39, v39
	v_exp_f32_e32 v40, v40
	v_exp_f32_e32 v41, v41
	v_exp_f32_e32 v38, v73
	v_add_f32_e32 v73, 0, v79
	v_cvt_pk_bf16_f32 v34, v79, v80
	v_cvt_pk_bf16_f32 v35, v81, v103
	v_pk_mul_f32 v[32:33], v[32:33], v[38:39] op_sel_hi:[1,0]
	v_pk_mul_f32 v[30:31], v[30:31], v[38:39] op_sel_hi:[1,0]
	v_pk_mul_f32 v[28:29], v[28:29], v[38:39] op_sel_hi:[1,0]
	v_pk_mul_f32 v[26:27], v[26:27], v[38:39] op_sel_hi:[1,0]
	v_pk_mul_f32 v[24:25], v[24:25], v[38:39] op_sel_hi:[1,0]
	v_pk_mul_f32 v[22:23], v[22:23], v[38:39] op_sel_hi:[1,0]
	v_pk_mul_f32 v[20:21], v[20:21], v[38:39] op_sel_hi:[1,0]
	v_pk_mul_f32 v[18:19], v[18:19], v[38:39] op_sel_hi:[1,0]
	v_pk_mul_f32 v[16:17], v[16:17], v[38:39] op_sel_hi:[1,0]
	v_cvt_pk_bf16_f32 v36, v104, v39
	v_cvt_pk_bf16_f32 v37, v40, v41
	v_pk_mul_f32 v[14:15], v[14:15], v[38:39] op_sel_hi:[1,0]
	v_pk_mul_f32 v[12:13], v[12:13], v[38:39] op_sel_hi:[1,0]
	v_pk_mul_f32 v[10:11], v[10:11], v[38:39] op_sel_hi:[1,0]
	v_pk_mul_f32 v[8:9], v[8:9], v[38:39] op_sel_hi:[1,0]
	v_pk_mul_f32 v[6:7], v[6:7], v[38:39] op_sel_hi:[1,0]
	v_pk_mul_f32 v[4:5], v[4:5], v[38:39] op_sel_hi:[1,0]
	v_pk_mul_f32 v[2:3], v[2:3], v[38:39] op_sel_hi:[1,0]
	v_add_f32_e32 v73, v80, v73
	v_mfma_f32_32x32x16_bf16 v[18:33], v[74:77], v[34:37], v[18:33]
	v_add_f32_e32 v73, v81, v73
	v_fma_f32 v42, v42, s18, -v78
	v_add_f32_e32 v73, v103, v73
	v_fma_f32 v43, v43, s18, -v78
	v_fma_f32 v44, v44, s18, -v78
	v_fma_f32 v45, v45, s18, -v78
	v_fma_f32 v46, v46, s18, -v78
	v_mfma_f32_32x32x16_bf16 v[2:17], v[90:93], v[34:37], v[2:17]
	v_fma_f32 v47, v47, s18, -v78
	v_fma_f32 v48, v48, s18, -v78
	v_fma_f32 v49, v49, s18, -v78
	v_exp_f32_e32 v42, v42
	v_add_f32_e32 v73, v104, v73
	v_exp_f32_e32 v43, v43
	v_exp_f32_e32 v44, v44
	v_exp_f32_e32 v45, v45
	v_exp_f32_e32 v46, v46
	v_exp_f32_e32 v47, v47
	v_exp_f32_e32 v48, v48
	v_exp_f32_e32 v49, v49
	v_add_f32_e32 v39, v39, v73
	v_add_f32_e32 v39, v40, v39
	v_add_f32_e32 v39, v41, v39
	v_add_f32_e32 v39, v42, v39
	v_cvt_pk_bf16_f32 v34, v42, v43
	v_cvt_pk_bf16_f32 v35, v44, v45
	v_cvt_pk_bf16_f32 v36, v46, v47
	v_cvt_pk_bf16_f32 v37, v48, v49
	v_add_f32_e32 v39, v43, v39
	v_mov_b32_e32 v73, v78
	v_mfma_f32_32x32x16_bf16 v[18:33], v[86:89], v[34:37], v[18:33]
	v_mfma_f32_32x32x16_bf16 v[2:17], v[94:97], v[34:37], v[2:17]
	v_add_f32_e32 v34, v44, v39
	v_add_f32_e32 v34, v45, v34
	v_add_f32_e32 v34, v46, v34
	v_add_f32_e32 v34, v47, v34
	v_add_f32_e32 v34, v48, v34
	v_add_f32_e32 v34, v49, v34
	v_mov_b32_e32 v35, v34
	s_nop 1
	v_permlane32_swap_b32_e32 v34, v35
	s_waitcnt lgkmcnt(0)
	v_add_f32_e32 v74, v34, v35
	v_fmac_f32_e32 v74, v85, v38
	s_cbranch_scc0 .LBB0_190
	s_and_b64 s[12:13], s[4:5], exec
	s_movk_i32 s1, 0x1a00
	s_cselect_b32 s12, 0x1200, s1
	s_mov_b32 s13, s31
	v_lshl_add_u64 v[34:35], v[68:69], 0, s[12:13]
	s_lshl_b64 s[12:13], s[30:31], 1
	v_lshl_add_u64 v[36:37], v[34:35], 0, s[12:13]
	v_lshlrev_b64 v[34:35], 11, v[66:67]
	s_and_b64 s[4:5], s[4:5], exec
	s_movk_i32 s1, 0x600
	v_lshl_add_u64 v[34:35], s[8:9], 0, v[34:35]
	s_cselect_b32 s30, 0x400, s1
	v_lshl_add_u64 v[34:35], v[34:35], 0, s[30:31]
	v_lshl_add_u64 v[38:39], v[34:35], 0, s[12:13]
	v_div_scale_f32 v34, s[4:5], v74, v74, 1.0
	v_rcp_f32_e32 v35, v34
	v_mov_b32_e32 v103, v1
	v_lshl_add_u64 v[36:37], v[36:37], 0, v[102:103]
	s_lshl_b32 s2, s58, 8
	v_fma_f32 v40, -v34, v35, 1.0
	v_fmac_f32_e32 v35, v40, v35
	v_div_scale_f32 v40, vcc, 1.0, v74, 1.0
	v_mul_f32_e32 v41, v40, v35
	v_fma_f32 v42, -v34, v41, v40
	v_fmac_f32_e32 v41, v42, v35
	v_fma_f32 v34, -v34, v41, v40
	v_div_fmas_f32 v34, v34, v35, v41
	global_load_dwordx2 v[40:41], v[36:37], off
	v_div_fixup_f32 v34, v34, v74, 1.0
	s_ashr_i32 s13, s58, 6
	s_bfe_u32 s1, s58, 0x20004
	s_lshl_b32 s30, s1, 7
	v_readlane_b32 s44, v255, 20
	v_readlane_b32 s45, v255, 21
	s_mov_b64 s[22:23], s[44:45]
	v_readlane_b32 s46, v255, 22
	v_readlane_b32 s47, v255, 23
	v_readlane_b32 s48, v255, 24
	v_readlane_b32 s49, v255, 25
	v_readlane_b32 s50, v255, 26
	v_readlane_b32 s51, v255, 27
	s_waitcnt vmcnt(0)
	v_lshlrev_b32_e32 v35, 16, v40
	v_and_b32_e32 v40, 0xffff0000, v40
	v_mul_f32_e32 v42, 0xbfb8aa3b, v35
	v_mul_f32_e32 v43, 0xbfb8aa3b, v40
	v_exp_f32_e32 v42, v42
	v_exp_f32_e32 v43, v43
	v_pk_mul_f32 v[18:19], v[18:19], v[34:35] op_sel_hi:[1,0]
	v_pk_add_f32 v[42:43], v[42:43], 1.0 op_sel_hi:[1,0]
	s_nop 0
	v_div_scale_f32 v44, s[4:5], v43, v43, v40
	v_rcp_f32_e32 v45, v44
	s_nop 0
	v_fma_f32 v46, -v44, v45, 1.0
	v_fmac_f32_e32 v45, v46, v45
	v_div_scale_f32 v46, vcc, v40, v43, v40
	v_mul_f32_e32 v47, v46, v45
	v_fma_f32 v48, -v44, v47, v46
	v_fmac_f32_e32 v47, v48, v45
	v_fma_f32 v44, -v44, v47, v46
	v_div_fmas_f32 v44, v44, v45, v47
	v_div_fixup_f32 v43, v44, v43, v40
	v_div_scale_f32 v40, s[4:5], v42, v42, v35
	v_rcp_f32_e32 v44, v40
	s_nop 0
	v_fma_f32 v45, -v40, v44, 1.0
	v_fmac_f32_e32 v44, v45, v44
	v_div_scale_f32 v45, vcc, v35, v42, v35
	v_mul_f32_e32 v46, v45, v44
	v_fma_f32 v47, -v40, v46, v45
	v_fmac_f32_e32 v46, v47, v44
	v_fma_f32 v40, -v40, v46, v45
	v_div_fmas_f32 v40, v40, v44, v46
	v_div_fixup_f32 v42, v40, v42, v35
	v_pk_mul_f32 v[18:19], v[18:19], v[42:43]
	v_lshlrev_b32_e32 v35, 16, v41
	v_and_b32_e32 v42, 0xffff0000, v41
	v_mul_f32_e32 v40, 0xbfb8aa3b, v35
	v_mul_f32_e32 v41, 0xbfb8aa3b, v42
	v_exp_f32_e32 v40, v40
	v_exp_f32_e32 v41, v41
	v_pk_mul_f32 v[20:21], v[20:21], v[34:35] op_sel_hi:[1,0]
	v_pk_add_f32 v[40:41], v[40:41], 1.0 op_sel_hi:[1,0]
	s_nop 0
	v_div_scale_f32 v43, s[4:5], v41, v41, v42
	v_rcp_f32_e32 v44, v43
	s_nop 0
	v_fma_f32 v45, -v43, v44, 1.0
	v_fmac_f32_e32 v44, v45, v44
	v_div_scale_f32 v45, vcc, v42, v41, v42
	v_mul_f32_e32 v46, v45, v44
	v_fma_f32 v47, -v43, v46, v45
	v_fmac_f32_e32 v46, v47, v44
	v_fma_f32 v43, -v43, v46, v45
	v_div_fmas_f32 v43, v43, v44, v46
	v_div_fixup_f32 v41, v43, v41, v42
	v_div_scale_f32 v42, s[4:5], v40, v40, v35
	v_rcp_f32_e32 v43, v42
	s_nop 0
	v_fma_f32 v44, -v42, v43, 1.0
	v_fmac_f32_e32 v43, v44, v43
	v_div_scale_f32 v44, vcc, v35, v40, v35
	v_mul_f32_e32 v45, v44, v43
	v_fma_f32 v46, -v42, v45, v44
	v_fmac_f32_e32 v45, v46, v43
	v_fma_f32 v42, -v42, v45, v44
	v_div_fmas_f32 v42, v42, v43, v45
	v_div_fixup_f32 v40, v42, v40, v35
	v_pk_mul_f32 v[40:41], v[20:21], v[40:41]
	v_cvt_pk_bf16_f32 v20, v18, v19
	v_cvt_pk_bf16_f32 v21, v40, v41
	v_lshl_add_u64 v[18:19], v[38:39], 0, v[102:103]
	global_store_dwordx2 v[18:19], v[20:21], off
	global_load_dwordx2 v[38:39], v[36:37], off offset:16
	s_waitcnt vmcnt(0)
	v_lshlrev_b32_e32 v35, 16, v38
	v_and_b32_e32 v38, 0xffff0000, v38
	v_mul_f32_e32 v20, 0xbfb8aa3b, v35
	v_mul_f32_e32 v21, 0xbfb8aa3b, v38
	v_exp_f32_e32 v20, v20
	v_exp_f32_e32 v21, v21
	v_pk_mul_f32 v[22:23], v[22:23], v[34:35] op_sel_hi:[1,0]
	v_pk_add_f32 v[20:21], v[20:21], 1.0 op_sel_hi:[1,0]
	s_nop 0
	v_div_scale_f32 v40, s[4:5], v21, v21, v38
	v_rcp_f32_e32 v41, v40
	s_nop 0
	v_fma_f32 v42, -v40, v41, 1.0
	v_fmac_f32_e32 v41, v42, v41
	v_div_scale_f32 v42, vcc, v38, v21, v38
	v_mul_f32_e32 v43, v42, v41
	v_fma_f32 v44, -v40, v43, v42
	v_fmac_f32_e32 v43, v44, v41
	v_fma_f32 v40, -v40, v43, v42
	v_div_fmas_f32 v40, v40, v41, v43
	v_div_fixup_f32 v21, v40, v21, v38
	v_div_scale_f32 v38, s[4:5], v20, v20, v35
	v_rcp_f32_e32 v40, v38
	s_nop 0
	v_fma_f32 v41, -v38, v40, 1.0
	v_fmac_f32_e32 v40, v41, v40
	v_div_scale_f32 v41, vcc, v35, v20, v35
	v_mul_f32_e32 v42, v41, v40
	v_fma_f32 v43, -v38, v42, v41
	v_fmac_f32_e32 v42, v43, v40
	v_fma_f32 v38, -v38, v42, v41
	v_div_fmas_f32 v38, v38, v40, v42
	v_div_fixup_f32 v20, v38, v20, v35
	v_lshlrev_b32_e32 v35, 16, v39
	v_pk_mul_f32 v[20:21], v[22:23], v[20:21]
	v_and_b32_e32 v40, 0xffff0000, v39
	v_mul_f32_e32 v22, 0xbfb8aa3b, v35
	v_exp_f32_e32 v38, v22
	v_pk_mul_f32 v[22:23], v[24:25], v[34:35] op_sel_hi:[1,0]
	v_mul_f32_e32 v24, 0xbfb8aa3b, v40
	v_exp_f32_e32 v39, v24
	v_cvt_pk_bf16_f32 v20, v20, v21
	v_pk_add_f32 v[24:25], v[38:39], 1.0 op_sel_hi:[1,0]
	s_nop 0
	v_div_scale_f32 v38, s[4:5], v25, v25, v40
	v_rcp_f32_e32 v39, v38
	s_nop 0
	v_fma_f32 v41, -v38, v39, 1.0
	v_fmac_f32_e32 v39, v41, v39
	v_div_scale_f32 v41, vcc, v40, v25, v40
	v_mul_f32_e32 v42, v41, v39
	v_fma_f32 v43, -v38, v42, v41
	v_fmac_f32_e32 v42, v43, v39
	v_fma_f32 v38, -v38, v42, v41
	v_div_fmas_f32 v38, v38, v39, v42
	v_div_fixup_f32 v25, v38, v25, v40
	v_div_scale_f32 v38, s[4:5], v24, v24, v35
	v_rcp_f32_e32 v39, v38
	s_nop 0
	v_fma_f32 v40, -v38, v39, 1.0
	v_fmac_f32_e32 v39, v40, v39
	v_div_scale_f32 v40, vcc, v35, v24, v35
	v_mul_f32_e32 v41, v40, v39
	v_fma_f32 v42, -v38, v41, v40
	v_fmac_f32_e32 v41, v42, v39
	v_fma_f32 v38, -v38, v41, v40
	v_div_fmas_f32 v38, v38, v39, v41
	v_div_fixup_f32 v24, v38, v24, v35
	v_pk_mul_f32 v[22:23], v[22:23], v[24:25]
	s_nop 0
	v_cvt_pk_bf16_f32 v21, v22, v23
	global_store_dwordx2 v[18:19], v[20:21], off offset:16
	global_load_dwordx2 v[22:23], v[36:37], off offset:32
	s_waitcnt vmcnt(0)
	v_lshlrev_b32_e32 v35, 16, v22
	v_and_b32_e32 v22, 0xffff0000, v22
	v_mul_f32_e32 v20, 0xbfb8aa3b, v35
	v_mul_f32_e32 v21, 0xbfb8aa3b, v22
	v_exp_f32_e32 v20, v20
	v_exp_f32_e32 v21, v21
	v_pk_mul_f32 v[24:25], v[26:27], v[34:35] op_sel_hi:[1,0]
	v_pk_add_f32 v[20:21], v[20:21], 1.0 op_sel_hi:[1,0]
	s_nop 0
	v_div_scale_f32 v26, s[4:5], v21, v21, v22
	v_rcp_f32_e32 v27, v26
	s_nop 0
	v_fma_f32 v38, -v26, v27, 1.0
	v_fmac_f32_e32 v27, v38, v27
	v_div_scale_f32 v38, vcc, v22, v21, v22
	v_mul_f32_e32 v39, v38, v27
	v_fma_f32 v40, -v26, v39, v38
	v_fmac_f32_e32 v39, v40, v27
	v_fma_f32 v26, -v26, v39, v38
	v_div_fmas_f32 v26, v26, v27, v39
	v_div_fixup_f32 v21, v26, v21, v22
	v_div_scale_f32 v22, s[4:5], v20, v20, v35
	v_rcp_f32_e32 v26, v22
	s_nop 0
	v_fma_f32 v27, -v22, v26, 1.0
	v_fmac_f32_e32 v26, v27, v26
	v_div_scale_f32 v27, vcc, v35, v20, v35
	v_mul_f32_e32 v38, v27, v26
	v_fma_f32 v39, -v22, v38, v27
	v_fmac_f32_e32 v38, v39, v26
	v_fma_f32 v22, -v22, v38, v27
	v_div_fmas_f32 v22, v22, v26, v38
	v_div_fixup_f32 v20, v22, v20, v35
	v_lshlrev_b32_e32 v26, 16, v23
	v_and_b32_e32 v27, 0xffff0000, v23
	v_pk_mul_f32 v[20:21], v[24:25], v[20:21]
	v_mul_f32_e32 v22, 0xbfb8aa3b, v26
	v_mul_f32_e32 v25, 0xbfb8aa3b, v27
	v_exp_f32_e32 v24, v22
	v_exp_f32_e32 v25, v25
	v_pk_mul_f32 v[22:23], v[28:29], v[34:35] op_sel_hi:[1,0]
	v_cvt_pk_bf16_f32 v20, v20, v21
	v_pk_add_f32 v[24:25], v[24:25], 1.0 op_sel_hi:[1,0]
	s_nop 0
	v_div_scale_f32 v28, s[4:5], v25, v25, v27
	v_rcp_f32_e32 v29, v28
	s_nop 0
	v_fma_f32 v35, -v28, v29, 1.0
	v_fmac_f32_e32 v29, v35, v29
	v_div_scale_f32 v35, vcc, v27, v25, v27
	v_mul_f32_e32 v38, v35, v29
	v_fma_f32 v39, -v28, v38, v35
	v_fmac_f32_e32 v38, v39, v29
	v_fma_f32 v28, -v28, v38, v35
	v_div_fmas_f32 v28, v28, v29, v38
	v_div_fixup_f32 v25, v28, v25, v27
	v_div_scale_f32 v27, s[4:5], v24, v24, v26
	v_rcp_f32_e32 v28, v27
	s_nop 0
	v_fma_f32 v29, -v27, v28, 1.0
	v_fmac_f32_e32 v28, v29, v28
	v_div_scale_f32 v29, vcc, v26, v24, v26
	v_mul_f32_e32 v35, v29, v28
	v_fma_f32 v38, -v27, v35, v29
	v_fmac_f32_e32 v35, v38, v28
	v_fma_f32 v27, -v27, v35, v29
	v_div_fmas_f32 v27, v27, v28, v35
	v_div_fixup_f32 v24, v27, v24, v26
	v_pk_mul_f32 v[22:23], v[22:23], v[24:25]
	v_pk_mul_f32 v[24:25], v[30:31], v[34:35] op_sel_hi:[1,0]
	v_cvt_pk_bf16_f32 v21, v22, v23
	global_store_dwordx2 v[18:19], v[20:21], off offset:32
	global_load_dwordx2 v[22:23], v[36:37], off offset:48
	v_pk_mul_f32 v[2:3], v[2:3], v[34:35] op_sel_hi:[1,0]
	v_pk_mul_f32 v[4:5], v[4:5], v[34:35] op_sel_hi:[1,0]
	v_pk_mul_f32 v[6:7], v[6:7], v[34:35] op_sel_hi:[1,0]
	s_waitcnt vmcnt(0)
	v_lshlrev_b32_e32 v26, 16, v22
	v_and_b32_e32 v22, 0xffff0000, v22
	v_mul_f32_e32 v20, 0xbfb8aa3b, v26
	v_mul_f32_e32 v21, 0xbfb8aa3b, v22
	v_exp_f32_e32 v20, v20
	v_exp_f32_e32 v21, v21
	s_nop 0
	v_pk_add_f32 v[20:21], v[20:21], 1.0 op_sel_hi:[1,0]
	s_nop 0
	v_div_scale_f32 v27, s[4:5], v21, v21, v22
	v_rcp_f32_e32 v28, v27
	s_nop 0
	v_fma_f32 v29, -v27, v28, 1.0
	v_fmac_f32_e32 v28, v29, v28
	v_div_scale_f32 v29, vcc, v22, v21, v22
	v_mul_f32_e32 v30, v29, v28
	v_fma_f32 v31, -v27, v30, v29
	v_fmac_f32_e32 v30, v31, v28
	v_fma_f32 v27, -v27, v30, v29
	v_div_fmas_f32 v27, v27, v28, v30
	v_div_fixup_f32 v21, v27, v21, v22
	v_div_scale_f32 v22, s[4:5], v20, v20, v26
	v_rcp_f32_e32 v27, v22
	s_nop 0
	v_fma_f32 v28, -v22, v27, 1.0
	v_fmac_f32_e32 v27, v28, v27
	v_div_scale_f32 v28, vcc, v26, v20, v26
	v_mul_f32_e32 v29, v28, v27
	v_fma_f32 v30, -v22, v29, v28
	v_fmac_f32_e32 v29, v30, v27
	v_fma_f32 v22, -v22, v29, v28
	v_div_fmas_f32 v22, v22, v27, v29
	v_div_fixup_f32 v20, v22, v20, v26
	v_lshlrev_b32_e32 v26, 16, v23
	v_and_b32_e32 v27, 0xffff0000, v23
	v_pk_mul_f32 v[20:21], v[24:25], v[20:21]
	v_mul_f32_e32 v22, 0xbfb8aa3b, v26
	v_mul_f32_e32 v25, 0xbfb8aa3b, v27
	v_exp_f32_e32 v24, v22
	v_exp_f32_e32 v25, v25
	v_pk_mul_f32 v[22:23], v[32:33], v[34:35] op_sel_hi:[1,0]
	v_cvt_pk_bf16_f32 v20, v20, v21
	v_pk_add_f32 v[24:25], v[24:25], 1.0 op_sel_hi:[1,0]
	s_nop 0
	v_div_scale_f32 v28, s[4:5], v25, v25, v27
	v_rcp_f32_e32 v29, v28
	s_nop 0
	v_fma_f32 v30, -v28, v29, 1.0
	v_fmac_f32_e32 v29, v30, v29
	v_div_scale_f32 v30, vcc, v27, v25, v27
	v_mul_f32_e32 v31, v30, v29
	v_fma_f32 v32, -v28, v31, v30
	v_fmac_f32_e32 v31, v32, v29
	v_fma_f32 v28, -v28, v31, v30
	v_div_fmas_f32 v28, v28, v29, v31
	v_div_fixup_f32 v25, v28, v25, v27
	v_div_scale_f32 v27, s[4:5], v24, v24, v26
	v_rcp_f32_e32 v28, v27
	s_nop 0
	v_fma_f32 v29, -v27, v28, 1.0
	v_fmac_f32_e32 v28, v29, v28
	v_div_scale_f32 v29, vcc, v26, v24, v26
	v_mul_f32_e32 v30, v29, v28
	v_fma_f32 v31, -v27, v30, v29
	v_fmac_f32_e32 v30, v31, v28
	v_fma_f32 v27, -v27, v30, v29
	v_div_fmas_f32 v27, v27, v28, v30
	v_div_fixup_f32 v24, v27, v24, v26
	v_pk_mul_f32 v[22:23], v[22:23], v[24:25]
	s_nop 0
	v_cvt_pk_bf16_f32 v21, v22, v23
	global_store_dwordx2 v[18:19], v[20:21], off offset:48
	global_load_dwordx2 v[20:21], v[36:37], off offset:64
	s_waitcnt vmcnt(0)
	v_lshlrev_b32_e32 v24, 16, v20
	v_and_b32_e32 v20, 0xffff0000, v20
	v_mul_f32_e32 v22, 0xbfb8aa3b, v24
	v_mul_f32_e32 v23, 0xbfb8aa3b, v20
	v_exp_f32_e32 v22, v22
	v_exp_f32_e32 v23, v23
	s_nop 0
	v_pk_add_f32 v[22:23], v[22:23], 1.0 op_sel_hi:[1,0]
	s_nop 0
	v_div_scale_f32 v25, s[4:5], v23, v23, v20
	v_rcp_f32_e32 v26, v25
	s_nop 0
	v_fma_f32 v27, -v25, v26, 1.0
	v_fmac_f32_e32 v26, v27, v26
	v_div_scale_f32 v27, vcc, v20, v23, v20
	v_mul_f32_e32 v28, v27, v26
	v_fma_f32 v29, -v25, v28, v27
	v_fmac_f32_e32 v28, v29, v26
	v_fma_f32 v25, -v25, v28, v27
	v_div_fmas_f32 v25, v25, v26, v28
	v_div_fixup_f32 v23, v25, v23, v20
	v_div_scale_f32 v20, s[4:5], v22, v22, v24
	v_rcp_f32_e32 v25, v20
	s_nop 0
	v_fma_f32 v26, -v20, v25, 1.0
	v_fmac_f32_e32 v25, v26, v25
	v_div_scale_f32 v26, vcc, v24, v22, v24
	v_mul_f32_e32 v27, v26, v25
	v_fma_f32 v28, -v20, v27, v26
	v_fmac_f32_e32 v27, v28, v25
	v_fma_f32 v20, -v20, v27, v26
	v_div_fmas_f32 v20, v20, v25, v27
	v_div_fixup_f32 v22, v20, v22, v24
	v_pk_mul_f32 v[2:3], v[2:3], v[22:23]
	v_lshlrev_b32_e32 v22, 16, v21
	v_and_b32_e32 v23, 0xffff0000, v21
	v_mul_f32_e32 v20, 0xbfb8aa3b, v22
	v_mul_f32_e32 v21, 0xbfb8aa3b, v23
	v_exp_f32_e32 v20, v20
	v_exp_f32_e32 v21, v21
	v_cvt_pk_bf16_f32 v2, v2, v3
	v_pk_add_f32 v[20:21], v[20:21], 1.0 op_sel_hi:[1,0]
	s_nop 0
	v_div_scale_f32 v24, s[4:5], v21, v21, v23
	v_rcp_f32_e32 v25, v24
	s_nop 0
	v_fma_f32 v26, -v24, v25, 1.0
	v_fmac_f32_e32 v25, v26, v25
	v_div_scale_f32 v26, vcc, v23, v21, v23
	v_mul_f32_e32 v27, v26, v25
	v_fma_f32 v28, -v24, v27, v26
	v_fmac_f32_e32 v27, v28, v25
	v_fma_f32 v24, -v24, v27, v26
	v_div_fmas_f32 v24, v24, v25, v27
	v_div_fixup_f32 v21, v24, v21, v23
	v_div_scale_f32 v23, s[4:5], v20, v20, v22
	v_rcp_f32_e32 v24, v23
	s_nop 0
	v_fma_f32 v25, -v23, v24, 1.0
	v_fmac_f32_e32 v24, v25, v24
	v_div_scale_f32 v25, vcc, v22, v20, v22
	v_mul_f32_e32 v26, v25, v24
	v_fma_f32 v27, -v23, v26, v25
	v_fmac_f32_e32 v26, v27, v24
	v_fma_f32 v23, -v23, v26, v25
	v_div_fmas_f32 v23, v23, v24, v26
	v_div_fixup_f32 v20, v23, v20, v22
	v_pk_mul_f32 v[4:5], v[4:5], v[20:21]
	s_nop 0
	v_cvt_pk_bf16_f32 v3, v4, v5
	global_store_dwordx2 v[18:19], v[2:3], off offset:64
	global_load_dwordx2 v[4:5], v[36:37], off offset:80
	s_waitcnt vmcnt(0)
	v_lshlrev_b32_e32 v20, 16, v4
	v_and_b32_e32 v4, 0xffff0000, v4
	v_mul_f32_e32 v2, 0xbfb8aa3b, v20
	v_mul_f32_e32 v3, 0xbfb8aa3b, v4
	v_exp_f32_e32 v2, v2
	v_exp_f32_e32 v3, v3
	s_nop 0
	v_pk_add_f32 v[2:3], v[2:3], 1.0 op_sel_hi:[1,0]
	s_nop 0
	v_div_scale_f32 v21, s[4:5], v3, v3, v4
	v_rcp_f32_e32 v22, v21
	s_nop 0
	v_fma_f32 v23, -v21, v22, 1.0
	v_fmac_f32_e32 v22, v23, v22
	v_div_scale_f32 v23, vcc, v4, v3, v4
	v_mul_f32_e32 v24, v23, v22
	v_fma_f32 v25, -v21, v24, v23
	v_fmac_f32_e32 v24, v25, v22
	v_fma_f32 v21, -v21, v24, v23
	v_div_fmas_f32 v21, v21, v22, v24
	v_div_fixup_f32 v3, v21, v3, v4
	v_div_scale_f32 v4, s[4:5], v2, v2, v20
	v_rcp_f32_e32 v21, v4
	s_nop 0
	v_fma_f32 v22, -v4, v21, 1.0
	v_fmac_f32_e32 v21, v22, v21
	v_div_scale_f32 v22, vcc, v20, v2, v20
	v_mul_f32_e32 v23, v22, v21
	v_fma_f32 v24, -v4, v23, v22
	v_fmac_f32_e32 v23, v24, v21
	v_fma_f32 v4, -v4, v23, v22
	v_div_fmas_f32 v4, v4, v21, v23
	v_div_fixup_f32 v2, v4, v2, v20
	v_lshlrev_b32_e32 v20, 16, v5
	v_and_b32_e32 v21, 0xffff0000, v5
	v_pk_mul_f32 v[2:3], v[6:7], v[2:3]
	v_mul_f32_e32 v4, 0xbfb8aa3b, v20
	v_mul_f32_e32 v7, 0xbfb8aa3b, v21
	v_exp_f32_e32 v6, v4
	v_exp_f32_e32 v7, v7
	v_pk_mul_f32 v[4:5], v[8:9], v[34:35] op_sel_hi:[1,0]
	v_cvt_pk_bf16_f32 v2, v2, v3
	v_pk_add_f32 v[6:7], v[6:7], 1.0 op_sel_hi:[1,0]
	s_nop 0
	v_div_scale_f32 v8, s[4:5], v7, v7, v21
	v_rcp_f32_e32 v9, v8
	s_nop 0
	v_fma_f32 v22, -v8, v9, 1.0
	v_fmac_f32_e32 v9, v22, v9
	v_div_scale_f32 v22, vcc, v21, v7, v21
	v_mul_f32_e32 v23, v22, v9
	v_fma_f32 v24, -v8, v23, v22
	v_fmac_f32_e32 v23, v24, v9
	v_fma_f32 v8, -v8, v23, v22
	v_div_fmas_f32 v8, v8, v9, v23
	v_div_fixup_f32 v7, v8, v7, v21
	v_div_scale_f32 v8, s[4:5], v6, v6, v20
	v_rcp_f32_e32 v9, v8
	s_nop 0
	v_fma_f32 v21, -v8, v9, 1.0
	v_fmac_f32_e32 v9, v21, v9
	v_div_scale_f32 v21, vcc, v20, v6, v20
	v_mul_f32_e32 v22, v21, v9
	v_fma_f32 v23, -v8, v22, v21
	v_fmac_f32_e32 v22, v23, v9
	v_fma_f32 v8, -v8, v22, v21
	v_div_fmas_f32 v8, v8, v9, v22
	v_div_fixup_f32 v6, v8, v6, v20
	v_pk_mul_f32 v[4:5], v[4:5], v[6:7]
	v_pk_mul_f32 v[6:7], v[10:11], v[34:35] op_sel_hi:[1,0]
	v_cvt_pk_bf16_f32 v3, v4, v5
	global_store_dwordx2 v[18:19], v[2:3], off offset:80
	global_load_dwordx2 v[4:5], v[36:37], off offset:96
	s_waitcnt vmcnt(0)
	v_lshlrev_b32_e32 v8, 16, v4
	v_and_b32_e32 v4, 0xffff0000, v4
	v_mul_f32_e32 v2, 0xbfb8aa3b, v8
	v_mul_f32_e32 v3, 0xbfb8aa3b, v4
	v_exp_f32_e32 v2, v2
	v_exp_f32_e32 v3, v3
	s_nop 0
	v_pk_add_f32 v[2:3], v[2:3], 1.0 op_sel_hi:[1,0]
	s_nop 0
	v_div_scale_f32 v9, s[4:5], v3, v3, v4
	v_rcp_f32_e32 v10, v9
	s_nop 0
	v_fma_f32 v11, -v9, v10, 1.0
	v_fmac_f32_e32 v10, v11, v10
	v_div_scale_f32 v11, vcc, v4, v3, v4
	v_mul_f32_e32 v20, v11, v10
	v_fma_f32 v21, -v9, v20, v11
	v_fmac_f32_e32 v20, v21, v10
	v_fma_f32 v9, -v9, v20, v11
	v_div_fmas_f32 v9, v9, v10, v20
	v_div_fixup_f32 v3, v9, v3, v4
	v_div_scale_f32 v4, s[4:5], v2, v2, v8
	v_rcp_f32_e32 v9, v4
	s_nop 0
	v_fma_f32 v10, -v4, v9, 1.0
	v_fmac_f32_e32 v9, v10, v9
	v_div_scale_f32 v10, vcc, v8, v2, v8
	v_mul_f32_e32 v11, v10, v9
	v_fma_f32 v20, -v4, v11, v10
	v_fmac_f32_e32 v11, v20, v9
	v_fma_f32 v4, -v4, v11, v10
	v_div_fmas_f32 v4, v4, v9, v11
	v_div_fixup_f32 v2, v4, v2, v8
	v_lshlrev_b32_e32 v8, 16, v5
	v_and_b32_e32 v9, 0xffff0000, v5
	v_pk_mul_f32 v[2:3], v[6:7], v[2:3]
	v_mul_f32_e32 v4, 0xbfb8aa3b, v8
	v_mul_f32_e32 v7, 0xbfb8aa3b, v9
	v_exp_f32_e32 v6, v4
	v_exp_f32_e32 v7, v7
	v_pk_mul_f32 v[4:5], v[12:13], v[34:35] op_sel_hi:[1,0]
	v_cvt_pk_bf16_f32 v2, v2, v3
	v_pk_add_f32 v[6:7], v[6:7], 1.0 op_sel_hi:[1,0]
	s_nop 0
	v_div_scale_f32 v10, s[4:5], v7, v7, v9
	v_rcp_f32_e32 v11, v10
	s_nop 0
	v_fma_f32 v12, -v10, v11, 1.0
	v_fmac_f32_e32 v11, v12, v11
	v_div_scale_f32 v12, vcc, v9, v7, v9
	v_mul_f32_e32 v13, v12, v11
	v_fma_f32 v20, -v10, v13, v12
	v_fmac_f32_e32 v13, v20, v11
	v_fma_f32 v10, -v10, v13, v12
	v_div_fmas_f32 v10, v10, v11, v13
	v_div_fixup_f32 v7, v10, v7, v9
	v_div_scale_f32 v9, s[4:5], v6, v6, v8
	v_rcp_f32_e32 v10, v9
	s_nop 0
	v_fma_f32 v11, -v9, v10, 1.0
	v_fmac_f32_e32 v10, v11, v10
	v_div_scale_f32 v11, vcc, v8, v6, v8
	v_mul_f32_e32 v12, v11, v10
	v_fma_f32 v13, -v9, v12, v11
	v_fmac_f32_e32 v12, v13, v10
	v_fma_f32 v9, -v9, v12, v11
	v_div_fmas_f32 v9, v9, v10, v12
	v_div_fixup_f32 v6, v9, v6, v8
	v_pk_mul_f32 v[4:5], v[4:5], v[6:7]
	v_pk_mul_f32 v[6:7], v[14:15], v[34:35] op_sel_hi:[1,0]
	v_cvt_pk_bf16_f32 v3, v4, v5
	global_store_dwordx2 v[18:19], v[2:3], off offset:96
	global_load_dwordx2 v[2:3], v[36:37], off offset:112
	s_waitcnt vmcnt(0)
	v_lshlrev_b32_e32 v8, 16, v2
	v_and_b32_e32 v2, 0xffff0000, v2
	v_mul_f32_e32 v4, 0xbfb8aa3b, v8
	v_mul_f32_e32 v5, 0xbfb8aa3b, v2
	v_exp_f32_e32 v4, v4
	v_exp_f32_e32 v5, v5
	s_nop 0
	v_pk_add_f32 v[4:5], v[4:5], 1.0 op_sel_hi:[1,0]
	s_nop 0
	v_div_scale_f32 v9, s[4:5], v5, v5, v2
	v_rcp_f32_e32 v10, v9
	s_nop 0
	v_fma_f32 v11, -v9, v10, 1.0
	v_fmac_f32_e32 v10, v11, v10
	v_div_scale_f32 v11, vcc, v2, v5, v2
	v_mul_f32_e32 v12, v11, v10
	v_fma_f32 v13, -v9, v12, v11
	v_fmac_f32_e32 v12, v13, v10
	v_fma_f32 v9, -v9, v12, v11
	v_div_fmas_f32 v9, v9, v10, v12
	v_div_fixup_f32 v5, v9, v5, v2
	v_div_scale_f32 v2, s[4:5], v4, v4, v8
	v_rcp_f32_e32 v9, v2
	s_nop 0
	v_fma_f32 v10, -v2, v9, 1.0
	v_fmac_f32_e32 v9, v10, v9
	v_div_scale_f32 v10, vcc, v8, v4, v8
	v_mul_f32_e32 v11, v10, v9
	v_fma_f32 v12, -v2, v11, v10
	v_fmac_f32_e32 v11, v12, v9
	v_fma_f32 v2, -v2, v11, v10
	v_div_fmas_f32 v2, v2, v9, v11
	v_div_fixup_f32 v4, v2, v4, v8
	v_lshlrev_b32_e32 v8, 16, v3
	v_and_b32_e32 v9, 0xffff0000, v3
	v_mul_f32_e32 v2, 0xbfb8aa3b, v8
	v_mul_f32_e32 v3, 0xbfb8aa3b, v9
	v_exp_f32_e32 v2, v2
	v_exp_f32_e32 v3, v3
	v_pk_mul_f32 v[4:5], v[6:7], v[4:5]
	v_pk_mul_f32 v[6:7], v[16:17], v[34:35] op_sel_hi:[1,0]
	v_cvt_pk_bf16_f32 v4, v4, v5
	v_pk_add_f32 v[2:3], v[2:3], 1.0 op_sel_hi:[1,0]
	s_nop 0
	v_div_scale_f32 v10, s[4:5], v3, v3, v9
	v_rcp_f32_e32 v11, v10
	s_nop 0
	v_fma_f32 v12, -v10, v11, 1.0
	v_fmac_f32_e32 v11, v12, v11
	v_div_scale_f32 v12, vcc, v9, v3, v9
	v_mul_f32_e32 v13, v12, v11
	v_fma_f32 v14, -v10, v13, v12
	v_fmac_f32_e32 v13, v14, v11
	v_fma_f32 v10, -v10, v13, v12
	v_div_fmas_f32 v10, v10, v11, v13
	v_div_fixup_f32 v3, v10, v3, v9
	v_div_scale_f32 v9, s[4:5], v2, v2, v8
	v_rcp_f32_e32 v10, v9
	s_and_b32 s4, s2, 0xf00
	s_lshl_b32 s2, s13, 12
	s_addk_i32 s2, 0x1000
	v_fma_f32 v11, -v9, v10, 1.0
	v_fmac_f32_e32 v10, v11, v10
	v_div_scale_f32 v11, vcc, v8, v2, v8
	v_mul_f32_e32 v12, v11, v10
	v_fma_f32 v13, -v9, v12, v11
	v_fmac_f32_e32 v12, v13, v10
	v_fma_f32 v9, -v9, v12, v11
	v_div_fmas_f32 v9, v9, v10, v12
	v_div_fixup_f32 v2, v9, v2, v8
	v_pk_mul_f32 v[2:3], v[6:7], v[2:3]
	v_lshlrev_b32_e32 v6, 1, v102
	v_cvt_pk_bf16_f32 v5, v2, v3
	global_store_dwordx2 v[18:19], v[4:5], off offset:112
	v_add_u32_e32 v5, s4, v70
	v_or_b32_e32 v4, v5, v124
	v_add_u32_e32 v104, s2, v4
	v_mov_b64_e32 v[2:3], s[6:7]
	v_mad_i64_i32 v[106:107], s[20:21], v104, s19, v[2:3]
	v_lshl_add_u64 v[2:3], v[106:107], 0, s[30:31]
	v_mov_b32_e32 v7, v1
	v_lshl_add_u64 v[2:3], v[2:3], 0, v[6:7]
	s_barrier
	global_load_dwordx4 v[66:69], v[2:3], off offset:3584
	global_load_dwordx4 v[70:73], v[2:3], off offset:3616
	global_load_dwordx4 v[74:77], v[2:3], off offset:3648
	global_load_dwordx4 v[78:81], v[2:3], off offset:3680
	s_max_u32 s12, s4, 0x80
	s_min_u32 s4, s4, 0xe80
	s_sub_i32 s4, s4, s12
	s_addk_i32 s4, 0x200
	s_ashr_i32 s5, s4, 7
	s_cmp_gt_i32 s5, -4
	s_cbranch_scc0 .LBB0_211
	s_lshr_b32 s4, s4, 7
	s_lshr_b32 s30, s1, 1
	s_add_i32 s17, s4, 4
	s_lshl_b32 s4, s30, 6
	s_lshl_b32 s5, s13, 7
	s_or_b32 s4, s4, s5
	s_ashr_i32 s5, s4, 31
	s_lshl_b64 s[4:5], s[4:5], 13
	s_add_u32 s4, s76, s4
	s_addc_u32 s5, s77, s5
	s_lshl_b32 s13, s13, 3
	s_lshl_b32 s20, s34, 1
	s_add_i32 s13, s13, s20
	s_or_b32 s20, s13, s30
	s_ashr_i32 s21, s20, 31
	s_lshl_b64 s[20:21], s[20:21], 16
	s_mul_hi_i32 s13, s2, 0x1c00
	s_mulk_i32 s2, 0x1c00
	s_add_u32 s2, s6, s2
	s_addc_u32 s13, s7, s13
	s_lshl_b32 s30, s30, 7
	s_add_u32 s36, s2, s30
	s_addc_u32 s37, s13, 0
	s_add_u32 s20, s76, s20
	s_mov_b32 s79, s31
	s_addc_u32 s21, s77, s21
	s_lshl_b64 s[44:45], s[78:79], 2
	s_add_u32 s22, s22, s44
	s_addc_u32 s23, s23, s45
	s_lshl_b32 s2, s1, 2
	v_mov_b32_e32 v2, s2
	global_load_dword v22, v2, s[22:23]
	v_ashrrev_i32_e32 v18, 4, v100
	v_and_b32_e32 v16, 0xf0, v82
	v_mov_b32_e32 v17, v1
	v_ashrrev_i32_e32 v19, 31, v18
	s_movk_i32 s2, 0x110
	v_mul_lo_u32 v25, v18, s2
	v_lshlrev_b64 v[108:109], 13, v[18:19]
	v_lshlrev_b64 v[110:111], 10, v[18:19]
	v_lshl_add_u64 v[18:19], s[4:5], 0, v[16:17]
	s_mov_b64 s[4:5], 0xda00000
	v_lshl_add_u64 v[116:117], v[18:19], 0, s[4:5]
	v_lshl_add_u64 v[18:19], s[36:37], 0, v[0:1]
	v_ashrrev_i32_e32 v20, 4, v83
	v_mov_b32_e32 v14, v1
	v_mov_b32_e32 v15, v1
	v_lshl_add_u64 v[118:119], v[18:19], 0, s[24:25]
	v_lshl_add_u64 v[18:19], s[20:21], 0, v[0:1]
	s_mov_b64 s[4:5], 0xe200000
	v_add_u32_e32 v103, 0xffffff80, v5
	v_add_u32_e32 v129, 0x9f, v5
	v_add_u32_e32 v134, 0xffffff80, v4
	v_add_u32_e32 v135, 0x80, v4
	v_mul_u32_u24_e32 v23, 0x110, v124
	v_mov_b32_e32 v2, v1
	v_mov_b32_e32 v3, v1
	v_mov_b32_e32 v4, v1
	v_mov_b32_e32 v5, v1
	v_mov_b32_e32 v6, v1
	v_mov_b32_e32 v7, v1
	v_mov_b32_e32 v8, v1
	v_mov_b32_e32 v9, v1
	v_mov_b32_e32 v10, v1
	v_mov_b32_e32 v11, v1
	v_mov_b32_e32 v12, v1
	v_mov_b32_e32 v13, v1
	v_add_u32_e32 v24, 0, v16
	v_ashrrev_i32_e32 v21, 31, v20
	v_mul_lo_u32 v26, v20, s2
	v_readlane_b32 s2, v255, 36
	v_lshl_add_u64 v[16:17], s[20:21], 0, v[16:17]
	v_mov_b32_e32 v0, v1
	v_lshl_add_u64 v[120:121], v[18:19], 0, s[4:5]
	s_mov_b64 s[4:5], 0xe300000
	v_mov_b64_e32 v[64:65], v[14:15]
	v_mov_b64_e32 v[48:49], v[14:15]
	v_add3_u32 v136, v84, v98, s0
	v_mov_b32_e32 v140, 1.0
	s_mov_b32 s0, 0
	v_add3_u32 v137, v23, v98, s2
	s_sext_i32_i16 s2, s17
	v_lshlrev_b64 v[112:113], 13, v[20:21]
	v_lshlrev_b64 v[114:115], 10, v[20:21]
	v_add_u32_e32 v138, v24, v25
	v_add_u32_e32 v139, v24, v26
	s_addk_i32 s12, 0xfd80
	v_lshl_add_u64 v[122:123], v[16:17], 0, s[4:5]
	v_mov_b64_e32 v[62:63], v[12:13]
	v_mov_b64_e32 v[60:61], v[10:11]
	v_mov_b64_e32 v[58:59], v[8:9]
	v_mov_b64_e32 v[56:57], v[6:7]
	v_mov_b64_e32 v[54:55], v[4:5]
	v_mov_b64_e32 v[52:53], v[2:3]
	v_mov_b64_e32 v[50:51], v[0:1]
	v_mov_b64_e32 v[46:47], v[12:13]
	v_mov_b64_e32 v[44:45], v[10:11]
	v_mov_b64_e32 v[42:43], v[8:9]
	v_mov_b64_e32 v[40:41], v[6:7]
	v_mov_b64_e32 v[38:39], v[4:5]
	v_mov_b64_e32 v[36:37], v[2:3]
	v_mov_b64_e32 v[34:35], v[0:1]
	v_lshlrev_b32_e32 v228, 7, v105
	v_add_u32_e32 v196, v228, v120
	v_subrev_u32_e32 v196, s56, v196
	v_lshlrev_b32_e32 v228, 7, v127
	v_add_u32_e32 v198, v228, v120
	v_subrev_u32_e32 v198, s56, v198
	v_add_u32_e32 v197, v122, v110
	v_subrev_u32_e32 v197, s56, v197
	v_add_u32_e32 v199, v122, v114
	v_subrev_u32_e32 v199, s56, v199
	s_add_i32 s4, s12, 0x200
	v_add_u32_e32 v228, s4, v105
	v_mul_u32_u24_e32 v228, 0x1c00, v228
	v_add_u32_e32 v200, v228, v118
	v_subrev_u32_e32 v200, s56, v200
	v_add_u32_e32 v228, s4, v127
	v_mul_u32_u24_e32 v228, 0x1c00, v228
	v_add_u32_e32 v202, v228, v118
	v_subrev_u32_e32 v202, s56, v202
	s_lshl_b32 s4, s4, 1
	v_add_u32_e32 v201, v116, v108
	v_add_u32_e32 v201, s4, v201
	v_subrev_u32_e32 v201, s56, v201
	v_add_u32_e32 v203, v116, v112
	v_add_u32_e32 v203, s4, v203
	v_subrev_u32_e32 v203, s56, v203
	global_load_dwordx4 v[204:207], v196, s[56:57]
	global_load_dwordx4 v[208:211], v197, s[56:57]
	global_load_dwordx4 v[212:215], v198, s[56:57]
	global_load_dwordx4 v[216:219], v199, s[56:57]
	v_add_u32_e32 v196, 0x4000, v196
	v_add_u32_e32 v198, 0x4000, v198
	v_add_u32_e32 v197, 0x100, v197
	v_add_u32_e32 v199, 0x100, v199
	s_waitcnt vmcnt(0)
	v_mul_f32_e32 v143, 0x3fb8aa3b, v22

.LBB0_203:
	s_add_i32 s4, s82, s13
	s_add_i32 s5, s4, 31
	v_cmp_ge_i32_e32 vcc, s5, v103
	v_cmp_le_i32_e64 s[4:5], s4, v129
	v_mov_b64_e32 v[18:19], v[50:51]
	v_mov_b64_e32 v[2:3], v[34:35]
	s_and_b64 s[4:5], vcc, s[4:5]
	v_mov_b64_e32 v[20:21], v[52:53]
	v_mov_b64_e32 v[22:23], v[54:55]
	v_mov_b64_e32 v[24:25], v[56:57]
	v_mov_b64_e32 v[26:27], v[58:59]
	v_mov_b64_e32 v[28:29], v[60:61]
	v_mov_b64_e32 v[30:31], v[62:63]
	v_mov_b64_e32 v[32:33], v[64:65]
	v_mov_b64_e32 v[4:5], v[36:37]
	v_mov_b64_e32 v[6:7], v[38:39]
	v_mov_b64_e32 v[8:9], v[40:41]
	v_mov_b64_e32 v[10:11], v[42:43]
	v_mov_b64_e32 v[12:13], v[44:45]
	v_mov_b64_e32 v[14:15], v[46:47]
	v_mov_b64_e32 v[16:17], v[48:49]
	v_mov_b32_e32 v144, v143
	v_mov_b32_e32 v145, v140
	s_and_saveexec_b64 s[84:85], s[4:5]
	s_cbranch_execz .LBB0_205
	ds_read_b128 v[2:5], v142
	ds_read_b128 v[18:21], v142 offset:32
	ds_read_b128 v[22:25], v142 offset:64
	ds_read_b128 v[26:29], v142 offset:96
	ds_read_b128 v[94:97], v141
	ds_read_b128 v[86:89], v141 offset:32
	ds_read_b128 v[90:93], v141 offset:8704
	ds_read_b128 v[82:85], v141 offset:8736
	s_waitcnt lgkmcnt(7)
	v_mfma_f32_32x32x16_bf16 v[2:17], v[2:5], v[66:69], 0
	s_waitcnt lgkmcnt(6)
	v_mfma_f32_32x32x16_bf16 v[2:17], v[18:21], v[70:73], v[2:17]
	v_add_u32_e32 v18, s13, v0
	v_cmp_ge_i32_e32 vcc, v18, v134
	v_cmp_le_i32_e64 s[4:5], v18, v135
	s_and_b64 vcc, vcc, s[4:5]
	v_add_u32_e32 v19, 1, v18
	v_cmp_lt_i32_e64 s[4:5], v18, v135
	v_add_u32_e32 v20, 2, v18
	s_waitcnt lgkmcnt(5)
	v_mfma_f32_32x32x16_bf16 v[2:17], v[22:25], v[74:77], v[2:17]
	s_waitcnt lgkmcnt(4)
	v_mfma_f32_32x32x16_bf16 v[2:17], v[26:29], v[78:81], v[2:17]
	s_nop 11
	v_mul_f32_e32 v2, 0x3e38aa3b, v2
	v_cndmask_b32_e32 v2, v186, v2, vcc
	v_cmp_ge_i32_e32 vcc, v19, v134
	s_and_b64 vcc, s[4:5], vcc
	v_mul_f32_e32 v3, 0x3e38aa3b, v3
	v_cndmask_b32_e32 v3, v186, v3, vcc
	v_cmp_ge_i32_e32 vcc, v20, v134
	v_cmp_le_i32_e64 s[4:5], v20, v135
	s_and_b64 vcc, vcc, s[4:5]
	v_mul_f32_e32 v4, 0x3e38aa3b, v4
	v_add_u32_e32 v20, 3, v18
	v_cndmask_b32_e32 v4, v186, v4, vcc
	v_cmp_ge_i32_e32 vcc, v20, v134
	v_cmp_le_i32_e64 s[4:5], v20, v135
	s_and_b64 vcc, vcc, s[4:5]
	v_mul_f32_e32 v5, 0x3e38aa3b, v5
	v_add_u32_e32 v20, 4, v18
	v_cndmask_b32_e32 v5, v186, v5, vcc
	v_cmp_ge_i32_e32 vcc, v20, v134
	v_cmp_le_i32_e64 s[4:5], v20, v135
	s_and_b64 vcc, vcc, s[4:5]
	v_mul_f32_e32 v6, 0x3e38aa3b, v6
	v_add_u32_e32 v20, 5, v18
	v_cndmask_b32_e32 v6, v186, v6, vcc
	v_cmp_ge_i32_e32 vcc, v20, v134
	v_cmp_le_i32_e64 s[4:5], v20, v135
	s_and_b64 vcc, vcc, s[4:5]
	v_mul_f32_e32 v7, 0x3e38aa3b, v7
	v_add_u32_e32 v20, 6, v18
	v_cndmask_b32_e32 v7, v186, v7, vcc
	v_cmp_ge_i32_e32 vcc, v20, v134
	v_cmp_le_i32_e64 s[4:5], v20, v135
	s_and_b64 vcc, vcc, s[4:5]
	v_mul_f32_e32 v8, 0x3e38aa3b, v8
	v_add_u32_e32 v20, 7, v18
	v_cndmask_b32_e32 v8, v186, v8, vcc
	v_cmp_ge_i32_e32 vcc, v20, v134
	v_cmp_le_i32_e64 s[4:5], v20, v135
	s_and_b64 vcc, vcc, s[4:5]
	v_mul_f32_e32 v9, 0x3e38aa3b, v9
	v_add_u32_e32 v20, 16, v18
	v_cndmask_b32_e32 v9, v186, v9, vcc
	v_cmp_ge_i32_e32 vcc, v20, v134
	v_cmp_le_i32_e64 s[4:5], v20, v135
	s_and_b64 vcc, vcc, s[4:5]
	v_mul_f32_e32 v10, 0x3e38aa3b, v10
	v_add_u32_e32 v20, 17, v18
	v_cndmask_b32_e32 v10, v186, v10, vcc
	v_cmp_ge_i32_e32 vcc, v20, v134
	v_cmp_le_i32_e64 s[4:5], v20, v135
	s_and_b64 vcc, vcc, s[4:5]
	v_mul_f32_e32 v11, 0x3e38aa3b, v11
	v_add_u32_e32 v20, 18, v18
	v_cndmask_b32_e32 v11, v186, v11, vcc
	v_cmp_ge_i32_e32 vcc, v20, v134
	v_cmp_le_i32_e64 s[4:5], v20, v135
	s_and_b64 vcc, vcc, s[4:5]
	v_mul_f32_e32 v12, 0x3e38aa3b, v12
	v_add_u32_e32 v20, 19, v18
	v_cndmask_b32_e32 v12, v186, v12, vcc
	v_cmp_ge_i32_e32 vcc, v20, v134
	v_cmp_le_i32_e64 s[4:5], v20, v135
	s_and_b64 vcc, vcc, s[4:5]
	v_mul_f32_e32 v13, 0x3e38aa3b, v13
	v_add_u32_e32 v20, 20, v18
	v_cndmask_b32_e32 v13, v186, v13, vcc
	v_cmp_ge_i32_e32 vcc, v20, v134
	v_cmp_le_i32_e64 s[4:5], v20, v135
	s_and_b64 vcc, vcc, s[4:5]
	v_mul_f32_e32 v14, 0x3e38aa3b, v14
	v_add_u32_e32 v20, 21, v18
	v_max3_f32 v19, v2, s52, v3
	v_cndmask_b32_e32 v14, v186, v14, vcc
	v_cmp_ge_i32_e32 vcc, v20, v134
	v_cmp_le_i32_e64 s[4:5], v20, v135
	v_max3_f32 v19, v19, v4, v5
	s_and_b64 vcc, vcc, s[4:5]
	v_mul_f32_e32 v15, 0x3e38aa3b, v15
	v_add_u32_e32 v20, 22, v18
	v_max3_f32 v19, v19, v6, v7
	v_cndmask_b32_e32 v15, v186, v15, vcc
	v_cmp_ge_i32_e32 vcc, v20, v134
	v_cmp_le_i32_e64 s[4:5], v20, v135
	v_max3_f32 v19, v19, v8, v9
	s_and_b64 vcc, vcc, s[4:5]
	v_mul_f32_e32 v16, 0x3e38aa3b, v16
	v_add_u32_e32 v18, 23, v18
	v_max3_f32 v19, v19, v10, v11
	v_cndmask_b32_e32 v16, v186, v16, vcc
	v_cmp_ge_i32_e32 vcc, v18, v134
	v_cmp_le_i32_e64 s[4:5], v18, v135
	v_max3_f32 v19, v19, v12, v13
	s_and_b64 vcc, vcc, s[4:5]
	v_mul_f32_e32 v17, 0x3e38aa3b, v17
	v_max3_f32 v19, v19, v14, v15
	v_cndmask_b32_e32 v17, v186, v17, vcc
	v_max3_f32 v18, v19, v16, v17
	v_mov_b32_e32 v19, v18
	s_nop 1
	v_permlane32_swap_b32_e32 v18, v19
	s_waitcnt lgkmcnt(0)
	v_max3_f32 v144, v143, v18, v19
	v_sub_f32_e32 v2, v2, v144
	v_exp_f32_e32 v146, v2
	v_sub_f32_e32 v3, v3, v144
	v_exp_f32_e32 v147, v3
	v_sub_f32_e32 v3, v4, v144
	v_exp_f32_e32 v148, v3
	v_sub_f32_e32 v3, v5, v144
	v_exp_f32_e32 v149, v3
	v_sub_f32_e32 v3, v6, v144
	v_add_f32_e32 v2, 0, v146
	v_exp_f32_e32 v150, v3
	v_sub_f32_e32 v3, v7, v144
	v_add_f32_e32 v2, v147, v2
	v_exp_f32_e32 v151, v3
	v_sub_f32_e32 v3, v8, v144
	v_add_f32_e32 v2, v148, v2
	v_exp_f32_e32 v152, v3
	v_sub_f32_e32 v3, v9, v144
	v_add_f32_e32 v2, v149, v2
	v_exp_f32_e32 v153, v3
	v_sub_f32_e32 v3, v10, v144
	v_add_f32_e32 v2, v150, v2
	v_exp_f32_e32 v154, v3
	v_sub_f32_e32 v3, v11, v144
	v_add_f32_e32 v2, v151, v2
	v_exp_f32_e32 v155, v3
	v_sub_f32_e32 v3, v12, v144
	v_add_f32_e32 v2, v152, v2
	v_exp_f32_e32 v156, v3
	v_sub_f32_e32 v3, v13, v144
	v_add_f32_e32 v2, v153, v2
	v_exp_f32_e32 v157, v3
	v_sub_f32_e32 v3, v14, v144
	v_add_f32_e32 v2, v154, v2
	v_exp_f32_e32 v158, v3
	v_sub_f32_e32 v3, v15, v144
	v_add_f32_e32 v2, v155, v2
	v_exp_f32_e32 v159, v3
	v_sub_f32_e32 v3, v16, v144
	v_add_f32_e32 v2, v156, v2
	v_exp_f32_e32 v160, v3
	v_sub_f32_e32 v3, v17, v144
	v_add_f32_e32 v2, v157, v2
	v_exp_f32_e32 v161, v3
	v_add_f32_e32 v2, v158, v2
	v_add_f32_e32 v2, v159, v2
	v_add_f32_e32 v2, v160, v2
	v_add_f32_e32 v3, v161, v2
	v_mov_b32_e32 v4, v3
	s_nop 1
	v_permlane32_swap_b32_e32 v3, v4
	v_sub_f32_e32 v18, v143, v144
	v_exp_f32_e32 v2, v18
	v_cvt_pk_bf16_f32 v146, v146, v147
	v_cvt_pk_bf16_f32 v147, v148, v149
	s_waitcnt lgkmcnt(0)
	v_add_f32_e32 v145, v3, v4
	v_fmac_f32_e32 v145, v140, v2
	v_pk_mul_f32 v[32:33], v[64:65], v[2:3] op_sel_hi:[1,0]
	v_pk_mul_f32 v[30:31], v[62:63], v[2:3] op_sel_hi:[1,0]
	v_pk_mul_f32 v[28:29], v[60:61], v[2:3] op_sel_hi:[1,0]
	v_pk_mul_f32 v[26:27], v[58:59], v[2:3] op_sel_hi:[1,0]
	v_pk_mul_f32 v[24:25], v[56:57], v[2:3] op_sel_hi:[1,0]
	v_pk_mul_f32 v[22:23], v[54:55], v[2:3] op_sel_hi:[1,0]
	v_pk_mul_f32 v[20:21], v[52:53], v[2:3] op_sel_hi:[1,0]
	v_pk_mul_f32 v[18:19], v[50:51], v[2:3] op_sel_hi:[1,0]
	v_pk_mul_f32 v[16:17], v[48:49], v[2:3] op_sel_hi:[1,0]
	v_pk_mul_f32 v[14:15], v[46:47], v[2:3] op_sel_hi:[1,0]
	v_pk_mul_f32 v[12:13], v[44:45], v[2:3] op_sel_hi:[1,0]
	v_pk_mul_f32 v[10:11], v[42:43], v[2:3] op_sel_hi:[1,0]
	v_pk_mul_f32 v[8:9], v[40:41], v[2:3] op_sel_hi:[1,0]
	v_pk_mul_f32 v[6:7], v[38:39], v[2:3] op_sel_hi:[1,0]
	v_pk_mul_f32 v[4:5], v[36:37], v[2:3] op_sel_hi:[1,0]
	v_pk_mul_f32 v[2:3], v[34:35], v[2:3] op_sel_hi:[1,0]
	v_cvt_pk_bf16_f32 v148, v150, v151
	v_cvt_pk_bf16_f32 v149, v152, v153
	s_nop 1
	v_mfma_f32_32x32x16_bf16 v[18:33], v[94:97], v[146:149], v[18:33]
	v_mfma_f32_32x32x16_bf16 v[2:17], v[90:93], v[146:149], v[2:17]
	v_cvt_pk_bf16_f32 v90, v154, v155
	v_cvt_pk_bf16_f32 v91, v156, v157
	v_cvt_pk_bf16_f32 v92, v158, v159
	v_cvt_pk_bf16_f32 v93, v160, v161
	s_nop 1
	v_mfma_f32_32x32x16_bf16 v[18:33], v[86:89], v[90:93], v[18:33]
	v_mfma_f32_32x32x16_bf16 v[2:17], v[82:85], v[90:93], v[2:17]

.LBB0_206:
	s_andn2_b64 vcc, exec, s[4:5]
	s_cbranch_vccnz .LBB0_208
	s_nop 7
	ds_read_b128 v[2:5], v142
	ds_read_b128 v[18:21], v142 offset:32
	s_waitcnt lgkmcnt(1)
	v_mfma_f32_32x32x16_bf16 v[2:17], v[2:5], v[66:69], 0
	s_waitcnt lgkmcnt(0)
	v_mfma_f32_32x32x16_bf16 v[2:17], v[18:21], v[70:73], v[2:17]
	ds_read_b128 v[18:21], v142 offset:64
	ds_read_b128 v[22:25], v142 offset:96
	ds_read_b128 v[82:85], v141
	ds_read_b128 v[86:89], v141 offset:32
	ds_read_b128 v[90:93], v141 offset:8704
	ds_read_b128 v[94:97], v141 offset:8736
	s_waitcnt lgkmcnt(5)
	v_mfma_f32_32x32x16_bf16 v[2:17], v[18:21], v[74:77], v[2:17]
	s_waitcnt lgkmcnt(4)
	v_mfma_f32_32x32x16_bf16 v[2:17], v[22:25], v[78:81], v[2:17]
	s_nop 11
	v_max3_f32 v18, v2, v3, v4
	v_max3_f32 v18, v18, v5, v6
	v_max3_f32 v18, v18, v7, v8
	v_max3_f32 v18, v18, v9, v10
	v_max3_f32 v18, v18, v11, v12
	v_max3_f32 v18, v18, v13, v14
	v_max3_f32 v18, v18, v15, v16
	v_max_f32_e32 v18, v18, v17
	v_mul_f32_e32 v18, 0x3e38aa3b, v18
	v_mov_b32_e32 v19, v18
	s_nop 1
	v_permlane32_swap_b32_e32 v18, v19
	s_waitcnt lgkmcnt(0)
	v_max3_f32 v144, v143, v18, v19
	v_fma_f32 v2, v2, s18, -v144
	v_fma_f32 v3, v3, s18, -v144
	v_exp_f32_e32 v2, v2
	v_fma_f32 v4, v4, s18, -v144
	v_exp_f32_e32 v3, v3
	v_fma_f32 v5, v5, s18, -v144
	v_exp_f32_e32 v4, v4
	v_fma_f32 v6, v6, s18, -v144
	v_fma_f32 v10, v10, s18, -v144
	v_exp_f32_e32 v5, v5
	v_sub_f32_e32 v18, v143, v144
	v_fma_f32 v7, v7, s18, -v144
	v_exp_f32_e32 v6, v6
	v_exp_f32_e32 v143, v10
	v_add_f32_e32 v10, 0, v2
	v_fma_f32 v8, v8, s18, -v144
	v_exp_f32_e32 v7, v7
	v_add_f32_e32 v10, v3, v10
	v_fma_f32 v9, v9, s18, -v144
	v_exp_f32_e32 v8, v8
	v_add_f32_e32 v10, v4, v10
	v_exp_f32_e32 v9, v9
	v_add_f32_e32 v10, v5, v10
	v_fma_f32 v11, v11, s18, -v144
	v_add_f32_e32 v10, v6, v10
	v_fma_f32 v12, v12, s18, -v144
	v_exp_f32_e32 v145, v11
	v_add_f32_e32 v10, v7, v10
	v_exp_f32_e32 v147, v12
	v_add_f32_e32 v10, v8, v10
	v_fma_f32 v11, v13, s18, -v144
	v_add_f32_e32 v10, v9, v10
	v_exp_f32_e32 v148, v11
	v_fma_f32 v11, v14, s18, -v144
	v_add_f32_e32 v10, v143, v10
	v_exp_f32_e32 v149, v11
	v_add_f32_e32 v10, v145, v10
	v_add_f32_e32 v10, v147, v10
	v_add_f32_e32 v10, v148, v10
	v_exp_f32_e32 v146, v18
	v_add_f32_e32 v150, v149, v10
	v_fma_f32 v10, v15, s18, -v144
	v_exp_f32_e32 v151, v10
	v_fma_f32 v10, v16, s18, -v144
	v_exp_f32_e32 v152, v10
	v_fma_f32 v10, v17, s18, -v144
	v_exp_f32_e32 v153, v10
	v_pk_mul_f32 v[32:33], v[64:65], v[146:147] op_sel_hi:[1,0]
	v_pk_mul_f32 v[30:31], v[62:63], v[146:147] op_sel_hi:[1,0]
	v_pk_mul_f32 v[28:29], v[60:61], v[146:147] op_sel_hi:[1,0]
	v_pk_mul_f32 v[26:27], v[58:59], v[146:147] op_sel_hi:[1,0]
	v_pk_mul_f32 v[24:25], v[56:57], v[146:147] op_sel_hi:[1,0]
	v_pk_mul_f32 v[22:23], v[54:55], v[146:147] op_sel_hi:[1,0]
	v_pk_mul_f32 v[20:21], v[52:53], v[146:147] op_sel_hi:[1,0]
	v_pk_mul_f32 v[18:19], v[50:51], v[146:147] op_sel_hi:[1,0]
	v_pk_mul_f32 v[16:17], v[48:49], v[146:147] op_sel_hi:[1,0]
	v_cvt_pk_bf16_f32 v48, v2, v3
	v_cvt_pk_bf16_f32 v49, v4, v5
	v_cvt_pk_bf16_f32 v50, v6, v7
	v_cvt_pk_bf16_f32 v51, v8, v9
	v_pk_mul_f32 v[14:15], v[46:47], v[146:147] op_sel_hi:[1,0]
	v_pk_mul_f32 v[12:13], v[44:45], v[146:147] op_sel_hi:[1,0]
	v_pk_mul_f32 v[10:11], v[42:43], v[146:147] op_sel_hi:[1,0]
	v_pk_mul_f32 v[8:9], v[40:41], v[146:147] op_sel_hi:[1,0]
	v_pk_mul_f32 v[6:7], v[38:39], v[146:147] op_sel_hi:[1,0]
	v_pk_mul_f32 v[4:5], v[36:37], v[146:147] op_sel_hi:[1,0]
	v_pk_mul_f32 v[2:3], v[34:35], v[146:147] op_sel_hi:[1,0]
	v_mfma_f32_32x32x16_bf16 v[18:33], v[82:85], v[48:51], v[18:33]
	v_add_f32_e32 v34, v151, v150
	v_add_f32_e32 v34, v152, v34
	v_add_f32_e32 v38, v153, v34
	v_cvt_pk_bf16_f32 v34, v143, v145
	v_cvt_pk_bf16_f32 v35, v147, v148
	v_cvt_pk_bf16_f32 v36, v149, v151
	v_cvt_pk_bf16_f32 v37, v152, v153
	v_mfma_f32_32x32x16_bf16 v[2:17], v[90:93], v[48:51], v[2:17]
	v_mov_b32_e32 v39, v38
	s_nop 1
	v_permlane32_swap_b32_e32 v38, v39
	s_waitcnt lgkmcnt(0)
	v_add_f32_e32 v145, v38, v39
	v_fmac_f32_e32 v145, v140, v146
	v_mfma_f32_32x32x16_bf16 v[18:33], v[86:89], v[34:37], v[18:33]
	v_mfma_f32_32x32x16_bf16 v[2:17], v[94:97], v[34:37], v[2:17]

.Lnb_ld_done:
	v_max3_f32 v118, v34, v35, v36
	v_max3_f32 v118, v118, v37, v38
	v_max3_f32 v118, v118, v39, v40
	v_max3_f32 v118, v118, v41, v42
	v_max3_f32 v118, v118, v43, v44
	v_max3_f32 v118, v118, v45, v46
	v_max3_f32 v118, v118, v47, v48
	v_max_f32_e32 v118, v118, v49
	v_mul_f32_e32 v118, 0x3e38aa3b, v118
	v_mov_b32_e32 v119, v118
	s_nop 1
	v_permlane32_swap_b32_e32 v118, v119
	s_waitcnt lgkmcnt(0)
	v_max3_f32 v118, v0, v118, v119
	v_fma_f32 v34, v34, s18, -v118
	v_exp_f32_e32 v34, v34
	v_fma_f32 v35, v35, s18, -v118
	v_exp_f32_e32 v35, v35
	v_fma_f32 v36, v36, s18, -v118
	v_exp_f32_e32 v36, v36
	v_fma_f32 v37, v37, s18, -v118
	v_exp_f32_e32 v37, v37
	v_fma_f32 v38, v38, s18, -v118
	v_add_f32_e32 v119, 0, v34
	v_exp_f32_e32 v38, v38
	v_fma_f32 v39, v39, s18, -v118
	v_sub_f32_e32 v0, v0, v118
	v_add_f32_e32 v119, v35, v119
	v_exp_f32_e32 v39, v39
	v_fma_f32 v40, v40, s18, -v118
	v_fma_f32 v41, v41, s18, -v118
	v_add_f32_e32 v119, v36, v119
	v_exp_f32_e32 v40, v40
	v_exp_f32_e32 v41, v41
	v_exp_f32_e32 v0, v0
	v_add_f32_e32 v119, v37, v119
	v_fma_f32 v42, v42, s18, -v118
	v_add_f32_e32 v119, v38, v119
	v_exp_f32_e32 v42, v42
	v_fma_f32 v43, v43, s18, -v118
	v_add_f32_e32 v119, v39, v119
	v_exp_f32_e32 v43, v43
	v_fma_f32 v44, v44, s18, -v118
	v_add_f32_e32 v119, v40, v119
	v_exp_f32_e32 v44, v44
	v_fma_f32 v45, v45, s18, -v118
	v_pk_mul_f32 v[32:33], v[32:33], v[0:1] op_sel_hi:[1,0]
	v_pk_mul_f32 v[30:31], v[30:31], v[0:1] op_sel_hi:[1,0]
	v_pk_mul_f32 v[28:29], v[28:29], v[0:1] op_sel_hi:[1,0]
	v_pk_mul_f32 v[26:27], v[26:27], v[0:1] op_sel_hi:[1,0]
	v_pk_mul_f32 v[24:25], v[24:25], v[0:1] op_sel_hi:[1,0]
	v_pk_mul_f32 v[22:23], v[22:23], v[0:1] op_sel_hi:[1,0]
	v_pk_mul_f32 v[20:21], v[20:21], v[0:1] op_sel_hi:[1,0]
	v_pk_mul_f32 v[18:19], v[18:19], v[0:1] op_sel_hi:[1,0]
	v_pk_mul_f32 v[16:17], v[16:17], v[0:1] op_sel_hi:[1,0]
	v_pk_mul_f32 v[14:15], v[14:15], v[0:1] op_sel_hi:[1,0]
	v_pk_mul_f32 v[12:13], v[12:13], v[0:1] op_sel_hi:[1,0]
	v_pk_mul_f32 v[10:11], v[10:11], v[0:1] op_sel_hi:[1,0]
	v_pk_mul_f32 v[8:9], v[8:9], v[0:1] op_sel_hi:[1,0]
	v_pk_mul_f32 v[6:7], v[6:7], v[0:1] op_sel_hi:[1,0]
	v_pk_mul_f32 v[4:5], v[4:5], v[0:1] op_sel_hi:[1,0]
	v_pk_mul_f32 v[2:3], v[2:3], v[0:1] op_sel_hi:[1,0]
	v_cvt_pk_bf16_f32 v34, v34, v35
	v_cvt_pk_bf16_f32 v35, v36, v37
	v_cvt_pk_bf16_f32 v36, v38, v39
	v_cvt_pk_bf16_f32 v37, v40, v41
	v_add_f32_e32 v119, v41, v119
	v_exp_f32_e32 v45, v45
	v_fma_f32 v46, v46, s18, -v118
	s_nop 0
	v_mfma_f32_32x32x16_bf16 v[18:33], v[78:81], v[34:37], v[18:33]
	v_add_f32_e32 v119, v42, v119
	v_exp_f32_e32 v46, v46
	v_fma_f32 v47, v47, s18, -v118
	v_add_f32_e32 v119, v43, v119
	v_exp_f32_e32 v47, v47
	v_fma_f32 v48, v48, s18, -v118
	v_fma_f32 v49, v49, s18, -v118
	s_nop 0
	v_mfma_f32_32x32x16_bf16 v[2:17], v[74:77], v[34:37], v[2:17]
	v_add_f32_e32 v119, v44, v119
	v_exp_f32_e32 v48, v48
	v_exp_f32_e32 v49, v49
	v_add_f32_e32 v119, v45, v119
	v_add_f32_e32 v119, v46, v119
	v_add_f32_e32 v119, v47, v119
	v_add_f32_e32 v119, v48, v119
	v_cvt_pk_bf16_f32 v34, v42, v43
	v_cvt_pk_bf16_f32 v35, v44, v45
	v_cvt_pk_bf16_f32 v36, v46, v47
	v_cvt_pk_bf16_f32 v37, v48, v49
	v_add_f32_e32 v119, v49, v119
	v_mov_b32_e32 v123, v119
	s_nop 1
	v_permlane32_swap_b32_e32 v119, v123
	v_mfma_f32_32x32x16_bf16 v[18:33], v[70:73], v[34:37], v[18:33]
	s_waitcnt lgkmcnt(0)
	v_add_f32_e32 v123, v119, v123
	v_fmac_f32_e32 v123, v97, v0
	v_mfma_f32_32x32x16_bf16 v[2:17], v[66:69], v[34:37], v[2:17]
	s_cmp_eq_u32 s0, 0
	s_cbranch_scc0 .LBB0_221
	v_sub_u32_e64 v0, v115, 4 clamp
	v_min_u32_e32 v105, 56, v0
	v_max_i32_e32 v0, 8, v116
	v_add_u32_e32 v0, -8, v0
	v_min_u32_e32 v119, 48, v0
	v_lshlrev_b32_e32 v0, 8, v121
	v_or3_b32 v0, v0, v100, v124
	s_movk_i32 s0, 0x744
	v_lshlrev_b64 v[34:35], 13, v[0:1]
	v_mad_u32_u24 v104, v120, s0, 0
	v_or_b32_e32 v120, v122, v124
	v_lshl_add_u64 v[106:107], v[86:87], 0, v[34:35]
	v_add_u32_e32 v121, 16, v119
	s_mov_b32 s0, 0
	s_mov_b32 s1, 0
	v_and_b32_e32 v36, 32, v116
	v_mul_u32_u24_e32 v37, 0x2300, v36
	v_sub_u32_e32 v196, v204, v37
	v_add_u32_e32 v196, 0xfff58000, v196
	v_add_u32_e32 v197, 0x70000, v196
	v_add_u32_e32 v198, 0xe0000, v196
	v_add_u32_e32 v199, 0x150000, v196
	v_and_b32_e32 v37, 3, v176
	v_mul_u32_u24_e32 v37, 0x70, v37
	v_add_u32_e32 v200, v208, v37
	v_lshrrev_b32_e32 v37, 5, v36
	v_mul_u32_u24_e32 v37, 0x50, v37
	v_sub_u32_e32 v200, v200, v37
	v_add_u32_e32 v200, 0xffffff40, v200
	v_add_u32_e32 v201, 0x20000, v200
	v_add_u32_e32 v202, 0x40000, v200
	v_add_u32_e32 v203, 0x60000, v200

.Lnb_l_cont:
	v_fma_f32 v34, v34, s18, v162
	v_fma_f32 v35, v35, s18, v163
	v_fma_f32 v36, v36, s18, v164
	v_fma_f32 v37, v37, s18, v165
	v_fma_f32 v38, v38, s18, v166
	v_fma_f32 v39, v39, s18, v167
	v_fma_f32 v40, v40, s18, v168
	v_fma_f32 v41, v41, s18, v169
	v_fma_f32 v42, v42, s18, v170
	v_fma_f32 v43, v43, s18, v171
	v_fma_f32 v44, v44, s18, v172
	v_fma_f32 v45, v45, s18, v173
	v_fma_f32 v46, v46, s18, v195
	v_fma_f32 v47, v47, s18, v244
	v_fma_f32 v48, v48, s18, v97
	v_fma_f32 v49, v49, s18, v123
	v_max3_f32 v97, v34, s52, v35
	v_max3_f32 v97, v97, v36, v37
	v_max3_f32 v97, v97, v38, v39
	v_max3_f32 v97, v97, v40, v41
	v_max3_f32 v97, v97, v42, v43
	v_max3_f32 v97, v97, v44, v45
	v_max3_f32 v97, v97, v46, v47
	v_max3_f32 v97, v97, v48, v49
	s_cmp_eq_u32 s1, 8
	v_mov_b32_e32 v108, v97
	s_nop 1
	v_permlane32_swap_b32_e32 v97, v108
	s_waitcnt lgkmcnt(0)
	v_max3_f32 v97, v118, v97, v108
	v_sub_f32_e32 v34, v34, v97
	v_exp_f32_e32 v109, v34
	v_sub_f32_e32 v35, v35, v97
	v_exp_f32_e32 v35, v35
	v_sub_f32_e32 v36, v36, v97
	v_exp_f32_e32 v36, v36
	v_sub_f32_e32 v37, v37, v97
	v_exp_f32_e32 v37, v37
	v_sub_f32_e32 v38, v38, v97
	v_add_f32_e32 v34, 0, v109
	v_exp_f32_e32 v38, v38
	v_sub_f32_e32 v39, v39, v97
	v_add_f32_e32 v34, v35, v34
	v_exp_f32_e32 v39, v39
	v_sub_f32_e32 v40, v40, v97
	v_add_f32_e32 v34, v36, v34
	v_exp_f32_e32 v40, v40
	v_sub_f32_e32 v41, v41, v97
	v_add_f32_e32 v34, v37, v34
	v_exp_f32_e32 v41, v41
	v_sub_f32_e32 v42, v42, v97
	v_add_f32_e32 v34, v38, v34
	v_exp_f32_e32 v42, v42
	v_sub_f32_e32 v43, v43, v97
	v_add_f32_e32 v34, v39, v34
	v_exp_f32_e32 v43, v43
	v_sub_f32_e32 v44, v44, v97
	v_add_f32_e32 v34, v40, v34
	v_exp_f32_e32 v44, v44
	v_sub_f32_e32 v45, v45, v97
	v_add_f32_e32 v34, v41, v34
	v_exp_f32_e32 v45, v45
	v_sub_f32_e32 v46, v46, v97
	v_add_f32_e32 v34, v42, v34
	v_exp_f32_e32 v46, v46
	v_sub_f32_e32 v47, v47, v97
	v_add_f32_e32 v34, v43, v34
	v_exp_f32_e32 v47, v47
	v_sub_f32_e32 v48, v48, v97
	v_add_f32_e32 v34, v44, v34
	v_exp_f32_e32 v48, v48
	v_sub_f32_e32 v49, v49, v97
	v_add_f32_e32 v34, v45, v34
	v_exp_f32_e32 v49, v49
	v_add_f32_e32 v34, v46, v34
	v_add_f32_e32 v34, v47, v34
	v_add_f32_e32 v34, v48, v34
	v_sub_f32_e32 v108, v118, v97
	v_add_f32_e32 v118, v49, v34
	v_exp_f32_e32 v34, v108
	v_mov_b32_e32 v108, v118
	s_nop 1
	v_permlane32_swap_b32_e32 v118, v108
	v_pk_mul_f32 v[32:33], v[32:33], v[34:35] op_sel_hi:[1,0]
	v_pk_mul_f32 v[30:31], v[30:31], v[34:35] op_sel_hi:[1,0]
	s_waitcnt lgkmcnt(0)
	v_add_f32_e32 v123, v118, v108
	v_fmac_f32_e32 v123, v122, v34
	v_pk_mul_f32 v[28:29], v[28:29], v[34:35] op_sel_hi:[1,0]
	v_pk_mul_f32 v[26:27], v[26:27], v[34:35] op_sel_hi:[1,0]
	v_pk_mul_f32 v[24:25], v[24:25], v[34:35] op_sel_hi:[1,0]
	v_pk_mul_f32 v[22:23], v[22:23], v[34:35] op_sel_hi:[1,0]
	v_pk_mul_f32 v[20:21], v[20:21], v[34:35] op_sel_hi:[1,0]
	v_pk_mul_f32 v[18:19], v[18:19], v[34:35] op_sel_hi:[1,0]
	v_pk_mul_f32 v[16:17], v[16:17], v[34:35] op_sel_hi:[1,0]
	v_pk_mul_f32 v[14:15], v[14:15], v[34:35] op_sel_hi:[1,0]
	v_pk_mul_f32 v[12:13], v[12:13], v[34:35] op_sel_hi:[1,0]
	v_pk_mul_f32 v[10:11], v[10:11], v[34:35] op_sel_hi:[1,0]
	v_pk_mul_f32 v[8:9], v[8:9], v[34:35] op_sel_hi:[1,0]
	v_pk_mul_f32 v[6:7], v[6:7], v[34:35] op_sel_hi:[1,0]
	v_pk_mul_f32 v[4:5], v[4:5], v[34:35] op_sel_hi:[1,0]
	v_pk_mul_f32 v[2:3], v[2:3], v[34:35] op_sel_hi:[1,0]
	v_cvt_pk_bf16_f32 v34, v109, v35
	v_cvt_pk_bf16_f32 v35, v36, v37
	v_cvt_pk_bf16_f32 v36, v38, v39
	v_cvt_pk_bf16_f32 v37, v40, v41
	v_mov_b32_e32 v118, v97
	s_nop 0
	v_mfma_f32_32x32x16_bf16 v[18:33], v[78:81], v[34:37], v[18:33]
	s_nop 0
	v_mfma_f32_32x32x16_bf16 v[2:17], v[74:77], v[34:37], v[2:17]
	v_cvt_pk_bf16_f32 v34, v42, v43
	v_cvt_pk_bf16_f32 v35, v44, v45
	v_cvt_pk_bf16_f32 v36, v46, v47
	v_cvt_pk_bf16_f32 v37, v48, v49
	s_nop 1
	v_mfma_f32_32x32x16_bf16 v[18:33], v[70:73], v[34:37], v[18:33]
	s_nop 0
	v_mfma_f32_32x32x16_bf16 v[2:17], v[66:69], v[34:37], v[2:17]
	s_cbranch_scc0 .LBB0_223
.Lnb_far:
	s_sub_i32 s2, s1, 8
	s_lshl_b32 s2, s2, 2
	v_add_u32_e32 v0, s2, v105
	v_sub_u32_e32 v0, v0, v115
	s_movk_i32 s4, 0x7c
	v_mad_u64_u32 v[108:109], s[4:5], v0, s4, v[104:105]
	v_lshlrev_b32_e32 v0, 1, v100
	v_mov_b32_e32 v122, v123
	v_and_b32_e32 v36, 32, v116
	v_lshrrev_b32_e32 v36, 2, v36
	v_sub_u32_e32 v36, 32, v36
	v_add_u32_e32 v36, v36, v82
	v_sub_u32_e32 v37, v36, v116
	v_add_u32_e32 v37, 15, v37
	v_lshl_add_u32 v108, v37, 2, v108
	v_sub_u32_e32 v36, v36, v119
	v_mov_b32_e32 v37, 0x1c98
	v_cmp_gt_u32_e32 vcc, 16, v36
	v_mov_b32_e32 v162, v108
	s_nop 0
	v_cndmask_b32_e32 v162, v37, v162, vcc
	ds_read_b32 v162, v162 offset:868
	v_add_u32_e32 v35, 1, v36
	v_cmp_gt_u32_e32 vcc, 16, v35
	v_add_u32_e32 v163, 4, v108
	s_nop 0
	v_cndmask_b32_e32 v163, v37, v163, vcc
	ds_read_b32 v163, v163 offset:868
	v_add_u32_e32 v35, 2, v36
	v_cmp_gt_u32_e32 vcc, 16, v35
	v_add_u32_e32 v164, 8, v108
	s_nop 0
	v_cndmask_b32_e32 v164, v37, v164, vcc
	ds_read_b32 v164, v164 offset:868
	v_add_u32_e32 v35, 3, v36
	v_cmp_gt_u32_e32 vcc, 16, v35
	v_add_u32_e32 v165, 12, v108
	s_nop 0
	v_cndmask_b32_e32 v165, v37, v165, vcc
	ds_read_b32 v165, v165 offset:868
	v_cmp_gt_u32_e32 vcc, 16, v36
	v_add_u32_e32 v166, 124, v108
	s_nop 0
	v_cndmask_b32_e32 v166, v37, v166, vcc
	ds_read_b32 v166, v166 offset:868
	v_add_u32_e32 v35, 1, v36
	v_cmp_gt_u32_e32 vcc, 16, v35
	v_add_u32_e32 v167, 128, v108
	s_nop 0
	v_cndmask_b32_e32 v167, v37, v167, vcc
	ds_read_b32 v167, v167 offset:868
	v_add_u32_e32 v35, 2, v36
	v_cmp_gt_u32_e32 vcc, 16, v35
	v_add_u32_e32 v168, 132, v108
	s_nop 0
	v_cndmask_b32_e32 v168, v37, v168, vcc
	ds_read_b32 v168, v168 offset:868
	v_add_u32_e32 v35, 3, v36
	v_cmp_gt_u32_e32 vcc, 16, v35
	v_add_u32_e32 v169, 136, v108
	s_nop 0
	v_cndmask_b32_e32 v169, v37, v169, vcc
	ds_read_b32 v169, v169 offset:868
	v_cmp_gt_u32_e32 vcc, 16, v36
	v_add_u32_e32 v170, 248, v108
	s_nop 0
	v_cndmask_b32_e32 v170, v37, v170, vcc
	ds_read_b32 v170, v170 offset:868
	v_add_u32_e32 v35, 1, v36
	v_cmp_gt_u32_e32 vcc, 16, v35
	v_add_u32_e32 v171, 252, v108
	s_nop 0
	v_cndmask_b32_e32 v171, v37, v171, vcc
	ds_read_b32 v171, v171 offset:868
	v_add_u32_e32 v35, 2, v36
	v_cmp_gt_u32_e32 vcc, 16, v35
	v_add_u32_e32 v172, 256, v108
	s_nop 0
	v_cndmask_b32_e32 v172, v37, v172, vcc
	ds_read_b32 v172, v172 offset:868
	v_add_u32_e32 v35, 3, v36
	v_cmp_gt_u32_e32 vcc, 16, v35
	v_add_u32_e32 v173, 260, v108
	s_nop 0
	v_cndmask_b32_e32 v173, v37, v173, vcc
	ds_read_b32 v173, v173 offset:868
	v_cmp_gt_u32_e32 vcc, 16, v36
	v_add_u32_e32 v195, 372, v108
	s_nop 0
	v_cndmask_b32_e32 v195, v37, v195, vcc
	ds_read_b32 v195, v195 offset:868
	v_add_u32_e32 v35, 1, v36
	v_cmp_gt_u32_e32 vcc, 16, v35
	v_add_u32_e32 v244, 376, v108
	s_nop 0
	v_cndmask_b32_e32 v244, v37, v244, vcc
	ds_read_b32 v244, v244 offset:868
	v_add_u32_e32 v35, 2, v36
	v_cmp_gt_u32_e32 vcc, 16, v35
	v_add_u32_e32 v97, 380, v108
	s_nop 0
	v_cndmask_b32_e32 v97, v37, v97, vcc
	ds_read_b32 v97, v97 offset:868
	v_add_u32_e32 v35, 3, v36
	v_cmp_gt_u32_e32 vcc, 16, v35
	v_add_u32_e32 v123, 384, v108
	s_nop 0
	v_cndmask_b32_e32 v123, v37, v123, vcc
	ds_read_b32 v123, v123 offset:868
	s_add_i32 s1, s1, 1
	ds_read_b128 v[248:251], v247
	ds_read_b128 v[126:129], v247 offset:32
	ds_read_b128 v[134:137], v247 offset:64
	ds_read_b128 v[138:141], v247 offset:96
	ds_read2_b64 v[78:81], v252 offset1:2
	ds_read2_b64 v[74:77], v253 offset1:2
	ds_read2_b64 v[70:73], v252 offset0:4 offset1:6
	ds_read2_b64 v[66:69], v253 offset0:4 offset1:6
	s_waitcnt vmcnt(0)
	ds_write_b128 v245, v[212:215]
	ds_write_b128 v245, v[216:219] offset:1152
	ds_write_b128 v245, v[220:223] offset:2304
	ds_write_b128 v245, v[224:227] offset:3456
	ds_write_b128 v246, v[228:231]
	ds_write_b128 v246, v[232:235] offset:1280
	ds_write_b128 v246, v[236:239] offset:2560
	ds_write_b128 v246, v[240:243] offset:3840
	s_waitcnt lgkmcnt(8)
	v_mfma_f32_32x32x16_bf16 v[34:49], v[248:251], v[58:61], 0
	v_mfma_f32_32x32x16_bf16 v[34:49], v[126:129], v[50:53], v[34:49]
	v_mfma_f32_32x32x16_bf16 v[34:49], v[134:137], v[54:57], v[34:49]
	v_mfma_f32_32x32x16_bf16 v[34:49], v[138:141], v[62:65], v[34:49]
	s_waitcnt lgkmcnt(0)
	s_nop 9
	v_fma_f32 v34, v34, s18, v162
	v_fma_f32 v35, v35, s18, v163
	v_fma_f32 v36, v36, s18, v164
	v_fma_f32 v37, v37, s18, v165
	v_fma_f32 v38, v38, s18, v166
	v_fma_f32 v39, v39, s18, v167
	v_fma_f32 v40, v40, s18, v168
	v_fma_f32 v41, v41, s18, v169
	v_fma_f32 v42, v42, s18, v170
	v_fma_f32 v43, v43, s18, v171
	v_fma_f32 v44, v44, s18, v172
	v_fma_f32 v45, v45, s18, v173
	v_fma_f32 v46, v46, s18, v195
	v_fma_f32 v47, v47, s18, v244
	v_fma_f32 v48, v48, s18, v97
	v_fma_f32 v49, v49, s18, v123
	v_max3_f32 v97, v34, s52, v35
	v_max3_f32 v97, v97, v36, v37
	v_max3_f32 v97, v97, v38, v39
	v_max3_f32 v97, v97, v40, v41
	v_max3_f32 v97, v97, v42, v43
	v_max3_f32 v97, v97, v44, v45
	v_max3_f32 v97, v97, v46, v47
	v_max3_f32 v97, v97, v48, v49
	s_cmp_eq_u32 s1, 10
	v_mov_b32_e32 v108, v97
	s_nop 1
	v_permlane32_swap_b32_e32 v97, v108
	s_waitcnt lgkmcnt(0)
	v_max3_f32 v97, v118, v97, v108
	v_sub_f32_e32 v34, v34, v97
	v_exp_f32_e32 v109, v34
	v_sub_f32_e32 v35, v35, v97
	v_exp_f32_e32 v35, v35
	v_sub_f32_e32 v36, v36, v97
	v_exp_f32_e32 v36, v36
	v_sub_f32_e32 v37, v37, v97
	v_exp_f32_e32 v37, v37
	v_sub_f32_e32 v38, v38, v97
	v_add_f32_e32 v34, 0, v109
	v_exp_f32_e32 v38, v38
	v_sub_f32_e32 v39, v39, v97
	v_add_f32_e32 v34, v35, v34
	v_exp_f32_e32 v39, v39
	v_sub_f32_e32 v40, v40, v97
	v_add_f32_e32 v34, v36, v34
	v_exp_f32_e32 v40, v40
	v_sub_f32_e32 v41, v41, v97
	v_add_f32_e32 v34, v37, v34
	v_exp_f32_e32 v41, v41
	v_sub_f32_e32 v42, v42, v97
	v_add_f32_e32 v34, v38, v34
	v_exp_f32_e32 v42, v42
	v_sub_f32_e32 v43, v43, v97
	v_add_f32_e32 v34, v39, v34
	v_exp_f32_e32 v43, v43
	v_sub_f32_e32 v44, v44, v97
	v_add_f32_e32 v34, v40, v34
	v_exp_f32_e32 v44, v44
	v_sub_f32_e32 v45, v45, v97
	v_add_f32_e32 v34, v41, v34
	v_exp_f32_e32 v45, v45
	v_sub_f32_e32 v46, v46, v97
	v_add_f32_e32 v34, v42, v34
	v_exp_f32_e32 v46, v46
	v_sub_f32_e32 v47, v47, v97
	v_add_f32_e32 v34, v43, v34
	v_exp_f32_e32 v47, v47
	v_sub_f32_e32 v48, v48, v97
	v_add_f32_e32 v34, v44, v34
	v_exp_f32_e32 v48, v48
	v_sub_f32_e32 v49, v49, v97
	v_add_f32_e32 v34, v45, v34
	v_exp_f32_e32 v49, v49
	v_add_f32_e32 v34, v46, v34
	v_add_f32_e32 v34, v47, v34
	v_add_f32_e32 v34, v48, v34
	v_sub_f32_e32 v108, v118, v97
	v_add_f32_e32 v118, v49, v34
	v_exp_f32_e32 v34, v108
	v_mov_b32_e32 v108, v118
	s_nop 1
	v_permlane32_swap_b32_e32 v118, v108
	v_pk_mul_f32 v[32:33], v[32:33], v[34:35] op_sel_hi:[1,0]
	v_pk_mul_f32 v[30:31], v[30:31], v[34:35] op_sel_hi:[1,0]
	s_waitcnt lgkmcnt(0)
	v_add_f32_e32 v123, v118, v108
	v_fmac_f32_e32 v123, v122, v34
	v_pk_mul_f32 v[28:29], v[28:29], v[34:35] op_sel_hi:[1,0]
	v_pk_mul_f32 v[26:27], v[26:27], v[34:35] op_sel_hi:[1,0]
	v_pk_mul_f32 v[24:25], v[24:25], v[34:35] op_sel_hi:[1,0]
	v_pk_mul_f32 v[22:23], v[22:23], v[34:35] op_sel_hi:[1,0]
	v_pk_mul_f32 v[20:21], v[20:21], v[34:35] op_sel_hi:[1,0]
	v_pk_mul_f32 v[18:19], v[18:19], v[34:35] op_sel_hi:[1,0]
	v_pk_mul_f32 v[16:17], v[16:17], v[34:35] op_sel_hi:[1,0]
	v_pk_mul_f32 v[14:15], v[14:15], v[34:35] op_sel_hi:[1,0]
	v_pk_mul_f32 v[12:13], v[12:13], v[34:35] op_sel_hi:[1,0]
	v_pk_mul_f32 v[10:11], v[10:11], v[34:35] op_sel_hi:[1,0]
	v_pk_mul_f32 v[8:9], v[8:9], v[34:35] op_sel_hi:[1,0]
	v_pk_mul_f32 v[6:7], v[6:7], v[34:35] op_sel_hi:[1,0]
	v_pk_mul_f32 v[4:5], v[4:5], v[34:35] op_sel_hi:[1,0]
	v_pk_mul_f32 v[2:3], v[2:3], v[34:35] op_sel_hi:[1,0]
	v_cvt_pk_bf16_f32 v34, v109, v35
	v_cvt_pk_bf16_f32 v35, v36, v37
	v_cvt_pk_bf16_f32 v36, v38, v39
	v_cvt_pk_bf16_f32 v37, v40, v41
	v_mov_b32_e32 v118, v97
	s_nop 0
	v_mfma_f32_32x32x16_bf16 v[18:33], v[78:81], v[34:37], v[18:33]
	s_nop 0
	v_mfma_f32_32x32x16_bf16 v[2:17], v[74:77], v[34:37], v[2:17]
	v_cvt_pk_bf16_f32 v34, v42, v43
	v_cvt_pk_bf16_f32 v35, v44, v45
	v_cvt_pk_bf16_f32 v36, v46, v47
	v_cvt_pk_bf16_f32 v37, v48, v49
	s_nop 1
	v_mfma_f32_32x32x16_bf16 v[18:33], v[70:73], v[34:37], v[18:33]
	s_nop 0
	v_mfma_f32_32x32x16_bf16 v[2:17], v[66:69], v[34:37], v[2:17]
	s_cbranch_scc0 .Lnb_far
	v_lshl_add_u64 v[34:35], v[102:103], 0, v[0:1]
	s_mov_b64 s[0:1], 0x1a00
	v_lshl_add_u64 v[36:37], v[34:35], 0, s[0:1]
